# G3 and G1 units: last K-loop iteration peeled without its final barrier so the leading half's epilogue and next first load segment overlap the trailing half's last MFMA block and epilogue (barrier cou
# baseline (speedup 1.0000x reference)
; #define PG8_STAGE(bufoff, gbase, voff) do { _Pragma("unroll") for (int _i = 0; _i < 2; ++_i) \
;         __builtin_amdgcn_global_load_lds((const unsigned*)((const char*)(gbase) + (voff)[_i]), (PG8_LAS unsigned*)(lds + (bufoff) + ldsw + _i * 8192), 16, 0, 0); } while (0)
; #define PG8_LDA(dst, b, h) do { _Pragma("unroll") for (int m = 0; m < 4; ++m) _Pragma("unroll") for (int k = 0; k < 2; ++k) dst[m][k] = *(const PG8_LAS bf16x8*)(lds + PG8_SA(b, h) + aoff + m * 2048 + k * 1024); } while (0)
; #define PG8_LDB(dst, b, h) do { _Pragma("unroll") for (int n = 0; n < 2; ++n) _Pragma("unroll") for (int k = 0; k < 2; ++k) dst[n][k] = *(const PG8_LAS bf16x8*)(lds + PG8_SB(b, h) + boff + n * 2048 + k * 1024); } while (0)
; #define PG8_MMA(ai, bj, At, Bt) do { __builtin_amdgcn_s_setprio(1); _Pragma("unroll") for (int m = 0; m < 4; ++m) _Pragma("unroll") for (int n = 0; n < 2; ++n) _Pragma("unroll") for (int k = 0; k < 2; ++k) \
;         acc[ai][bj][m][n] = __builtin_amdgcn_mfma_f32_16x16x32_bf16(Bt[n][k], At[m][k], acc[ai][bj][m][n], 0, 0, 0); __builtin_amdgcn_s_setprio(0); } while (0)
; #define PG8_WAIT_V(n) asm volatile("s_waitcnt vmcnt(" #n ")" ::: "memory")
; #define PG8_WAIT_L(n) asm volatile("s_waitcnt lgkmcnt(" #n ")" ::: "memory")
; #define PG8_BAR __builtin_amdgcn_s_barrier()
; #define PG8_SCHED __builtin_amdgcn_sched_barrier(0)
; template <class Epi, class Sched, bool ALIGN_EPI = false, bool SP2 = false>
; __device__ __forceinline__ void gemm_phase(PG8_LAS unsigned char* lds, const Gemm g, const Sched& S, const Epi& E) {
;     ...
;             if constexpr (SP2) {
;             PG8_LDB(B0, 0, 0); PG8_LDB(B1, 0, 1); PG8_SCHED; PG8_LDA(At, 0, 0); PG8_STAGE(PG8_SA(1, 1), a1 + hstep, voffA);
;             PG8_WAIT_V(8); PG8_WAIT_L(0); PG8_BAR; PG8_MMA(0, 0, At, B0); PG8_MMA(0, 1, At, B1); PG8_BAR; PG8_SCHED;
;             PG8_LDA(At, 0, 1); PG8_STAGE(PG8_SB(0, 0), b2, voffB); PG8_STAGE(PG8_SB(0, 1), b2 + hstep, voffB); PG8_STAGE(PG8_SA(0, 0), a2, voffA);
;             PG8_WAIT_V(8); PG8_WAIT_L(0); PG8_BAR; PG8_MMA(1, 0, At, B0); PG8_MMA(1, 1, At, B1); PG8_BAR; PG8_SCHED;
.Lsp_1:
	s_add_u32 s58, s72, 0xfffc0080
	s_addc_u32 s59, s73, -1
	s_add_i32 s84, 0, 0x10000
	s_cmp_eq_u32 s94, 12
	s_cselect_b32 s65, s36, s59
	s_cselect_b32 s64, s37, s58
	v_add_u32_e32 v140, s84, v146
	s_cselect_b32 s59, s51, s93
	s_cselect_b32 s58, s53, s92
	s_add_i32 s96, 0, 0x14000
	ds_read_b128 v[142:145], v140
	ds_read_b128 v[150:153], v140 offset:1024
	ds_read_b128 v[154:157], v140 offset:2048
	ds_read_b128 v[158:161], v140 offset:3072
	v_add_u32_e32 v140, s96, v146
	ds_read_b128 v[162:165], v140
	ds_read_b128 v[166:169], v140 offset:1024
	ds_read_b128 v[170:173], v140 offset:2048
	ds_read_b128 v[174:177], v140 offset:3072
	v_lshl_add_u64 v[186:187], s[72:73], 0, v[136:137]
	s_add_i32 m0, s19, 0xc000
	ds_read_b128 v[178:181], v148
	ds_read_b128 v[182:185], v148 offset:1024
	ds_read_b128 v[190:193], v148 offset:2048
	ds_read_b128 v[194:197], v148 offset:3072
	ds_read_b128 v[198:201], v148 offset:4096
	ds_read_b128 v[202:205], v148 offset:5120
	ds_read_b128 v[206:209], v148 offset:6144
	ds_read_b128 v[228:231], v148 offset:7168
	global_load_lds_dwordx4 v[186:187], off
	v_lshl_add_u64 v[186:187], s[72:73], 0, v[138:139]
	s_add_i32 m0, s19, 0xe000
	s_nop 0
	global_load_lds_dwordx4 v[186:187], off
	s_waitcnt vmcnt(8)
	s_waitcnt lgkmcnt(0)
	s_barrier
	s_waitcnt lgkmcnt(0)
	v_mfma_f32_16x16x32_bf16 v[124:127], v[142:145], v[178:181], 0
	v_mfma_f32_16x16x32_bf16 v[120:123], v[154:157], v[178:181], 0
	v_mfma_f32_16x16x32_bf16 v[116:119], v[142:145], v[190:193], 0
	v_mfma_f32_16x16x32_bf16 v[112:115], v[154:157], v[190:193], 0
	v_mfma_f32_16x16x32_bf16 v[108:111], v[142:145], v[198:201], 0
	v_mfma_f32_16x16x32_bf16 v[104:107], v[154:157], v[198:201], 0
	v_mfma_f32_16x16x32_bf16 v[100:103], v[142:145], v[206:209], 0
	v_mfma_f32_16x16x32_bf16 v[96:99], v[154:157], v[206:209], 0
	v_mfma_f32_16x16x32_bf16 v[124:127], v[150:153], v[182:185], v[124:127]
	v_mfma_f32_16x16x32_bf16 v[120:123], v[158:161], v[182:185], v[120:123]
	v_mfma_f32_16x16x32_bf16 v[116:119], v[150:153], v[194:197], v[116:119]
	v_mfma_f32_16x16x32_bf16 v[112:115], v[158:161], v[194:197], v[112:115]
	v_mfma_f32_16x16x32_bf16 v[108:111], v[150:153], v[202:205], v[108:111]
	v_mfma_f32_16x16x32_bf16 v[104:107], v[158:161], v[202:205], v[104:107]
	v_mfma_f32_16x16x32_bf16 v[100:103], v[150:153], v[228:231], v[100:103]
	v_mfma_f32_16x16x32_bf16 v[96:99], v[158:161], v[228:231], v[96:99]
	v_mfma_f32_16x16x32_bf16 v[92:95], v[162:165], v[178:181], 0
	v_mfma_f32_16x16x32_bf16 v[88:91], v[170:173], v[178:181], 0
	v_mfma_f32_16x16x32_bf16 v[84:87], v[162:165], v[190:193], 0
	v_mfma_f32_16x16x32_bf16 v[80:83], v[170:173], v[190:193], 0
	v_mfma_f32_16x16x32_bf16 v[76:79], v[162:165], v[198:201], 0
	v_mfma_f32_16x16x32_bf16 v[72:75], v[170:173], v[198:201], 0
	v_mfma_f32_16x16x32_bf16 v[68:71], v[162:165], v[206:209], 0
	v_mfma_f32_16x16x32_bf16 v[64:67], v[170:173], v[206:209], 0
	v_mfma_f32_16x16x32_bf16 v[92:95], v[166:169], v[182:185], v[92:95]
	v_mfma_f32_16x16x32_bf16 v[88:91], v[174:177], v[182:185], v[88:91]
	v_mfma_f32_16x16x32_bf16 v[84:87], v[166:169], v[194:197], v[84:87]
	v_mfma_f32_16x16x32_bf16 v[80:83], v[174:177], v[194:197], v[80:83]
	v_mfma_f32_16x16x32_bf16 v[76:79], v[166:169], v[202:205], v[76:79]
	v_mfma_f32_16x16x32_bf16 v[72:75], v[174:177], v[202:205], v[72:75]
	v_mfma_f32_16x16x32_bf16 v[68:71], v[166:169], v[228:231], v[68:71]
	v_mfma_f32_16x16x32_bf16 v[64:67], v[174:177], v[228:231], v[64:67]
	s_barrier
	s_add_i32 s84, s84, s18
	v_lshl_add_u64 v[186:187], s[58:59], 0, v[128:129]
	s_mov_b32 m0, s84
	ds_read_b128 v[178:181], v148 offset:16384
	ds_read_b128 v[182:185], v148 offset:17408
	ds_read_b128 v[190:193], v148 offset:18432
	ds_read_b128 v[194:197], v148 offset:19456
	ds_read_b128 v[198:201], v148 offset:20480
	ds_read_b128 v[202:205], v148 offset:21504
	ds_read_b128 v[206:209], v148 offset:22528
	ds_read_b128 v[228:231], v148 offset:23552
	global_load_lds_dwordx4 v[186:187], off
	s_add_i32 m0, s84, 0x2000
	s_add_u32 s84, s58, 0x40000
	v_lshl_add_u64 v[188:189], s[58:59], 0, v[130:131]
	s_addc_u32 s85, s59, 0
	s_add_i32 s96, s96, s18
	global_load_lds_dwordx4 v[188:189], off
	v_lshl_add_u64 v[210:211], s[84:85], 0, v[128:129]
	s_mov_b32 m0, s96
	v_lshl_add_u64 v[232:233], s[64:65], 0, v[132:133]
	global_load_lds_dwordx4 v[210:211], off
	v_lshl_add_u64 v[210:211], s[84:85], 0, v[130:131]
	s_add_i32 m0, s96, 0x2000
	s_nop 0
	global_load_lds_dwordx4 v[210:211], off
	v_lshl_add_u64 v[210:211], s[64:65], 0, v[134:135]
	s_mov_b32 m0, s19
	s_nop 0
	global_load_lds_dwordx4 v[210:211], off
	s_mov_b32 m0, s20
	s_nop 0
	global_load_lds_dwordx4 v[232:233], off
	s_waitcnt vmcnt(8)
	s_waitcnt lgkmcnt(0)
	s_barrier
; #define PG8_STAGE(bufoff, gbase, voff) do { _Pragma("unroll") for (int _i = 0; _i < 2; ++_i) \
;         __builtin_amdgcn_global_load_lds((const unsigned*)((const char*)(gbase) + (voff)[_i]), (PG8_LAS unsigned*)(lds + (bufoff) + ldsw + _i * 8192), 16, 0, 0); } while (0)
; #define PG8_LDA(dst, b, h) do { _Pragma("unroll") for (int m = 0; m < 4; ++m) _Pragma("unroll") for (int k = 0; k < 2; ++k) dst[m][k] = *(const PG8_LAS bf16x8*)(lds + PG8_SA(b, h) + aoff + m * 2048 + k * 1024); } while (0)
; #define PG8_LDB(dst, b, h) do { _Pragma("unroll") for (int n = 0; n < 2; ++n) _Pragma("unroll") for (int k = 0; k < 2; ++k) dst[n][k] = *(const PG8_LAS bf16x8*)(lds + PG8_SB(b, h) + boff + n * 2048 + k * 1024); } while (0)
; #define PG8_MMA(ai, bj, At, Bt) do { __builtin_amdgcn_s_setprio(1); _Pragma("unroll") for (int m = 0; m < 4; ++m) _Pragma("unroll") for (int n = 0; n < 2; ++n) _Pragma("unroll") for (int k = 0; k < 2; ++k) \
;         acc[ai][bj][m][n] = __builtin_amdgcn_mfma_f32_16x16x32_bf16(Bt[n][k], At[m][k], acc[ai][bj][m][n], 0, 0, 0); __builtin_amdgcn_s_setprio(0); } while (0)
; #define PG8_WAIT_V(n) asm volatile("s_waitcnt vmcnt(" #n ")" ::: "memory")
; #define PG8_WAIT_L(n) asm volatile("s_waitcnt lgkmcnt(" #n ")" ::: "memory")
; #define PG8_BAR __builtin_amdgcn_s_barrier()
; #define PG8_SCHED __builtin_amdgcn_sched_barrier(0)
; template <class Epi, class Sched, bool ALIGN_EPI = false, bool SP2 = false>
; __device__ __forceinline__ void gemm_phase(PG8_LAS unsigned char* lds, const Gemm g, const Sched& S, const Epi& E) {
;     ...
;             PG8_WAIT_V(8); PG8_WAIT_L(0); PG8_BAR; PG8_MMA(1, 0, At, B0); PG8_MMA(1, 1, At, B1); PG8_BAR; PG8_SCHED;
;             PG8_LDB(B0, 1, 0); PG8_LDB(B1, 1, 1); PG8_SCHED; PG8_LDA(At, 1, 0); PG8_STAGE(PG8_SA(0, 1), a2 + hstep, voffA);
;             PG8_WAIT_V(8); PG8_WAIT_L(0); PG8_BAR; PG8_MMA(0, 0, At, B0); PG8_MMA(0, 1, At, B1); PG8_BAR; PG8_SCHED;
	s_waitcnt lgkmcnt(0)
	v_mfma_f32_16x16x32_bf16 v[60:63], v[142:145], v[178:181], 0
	v_mfma_f32_16x16x32_bf16 v[56:59], v[154:157], v[178:181], 0
	v_mfma_f32_16x16x32_bf16 v[52:55], v[142:145], v[190:193], 0
	v_mfma_f32_16x16x32_bf16 v[48:51], v[154:157], v[190:193], 0
	v_mfma_f32_16x16x32_bf16 v[44:47], v[142:145], v[198:201], 0
	v_mfma_f32_16x16x32_bf16 v[40:43], v[154:157], v[198:201], 0
	v_mfma_f32_16x16x32_bf16 v[36:39], v[142:145], v[206:209], 0
	v_mfma_f32_16x16x32_bf16 v[32:35], v[154:157], v[206:209], 0
	v_mfma_f32_16x16x32_bf16 v[60:63], v[150:153], v[182:185], v[60:63]
	v_mfma_f32_16x16x32_bf16 v[56:59], v[158:161], v[182:185], v[56:59]
	v_mfma_f32_16x16x32_bf16 v[52:55], v[150:153], v[194:197], v[52:55]
	v_mfma_f32_16x16x32_bf16 v[48:51], v[158:161], v[194:197], v[48:51]
	v_mfma_f32_16x16x32_bf16 v[44:47], v[150:153], v[202:205], v[44:47]
	v_mfma_f32_16x16x32_bf16 v[40:43], v[158:161], v[202:205], v[40:43]
	v_mfma_f32_16x16x32_bf16 v[36:39], v[150:153], v[228:231], v[36:39]
	v_mfma_f32_16x16x32_bf16 v[32:35], v[158:161], v[228:231], v[32:35]
	v_mfma_f32_16x16x32_bf16 v[28:31], v[162:165], v[178:181], 0
	v_mfma_f32_16x16x32_bf16 v[24:27], v[170:173], v[178:181], 0
	v_mfma_f32_16x16x32_bf16 v[20:23], v[162:165], v[190:193], 0
	v_mfma_f32_16x16x32_bf16 v[16:19], v[170:173], v[190:193], 0
	v_mfma_f32_16x16x32_bf16 v[12:15], v[162:165], v[198:201], 0
	v_mfma_f32_16x16x32_bf16 v[8:11], v[170:173], v[198:201], 0
	v_mfma_f32_16x16x32_bf16 v[4:7], v[162:165], v[206:209], 0
	v_mfma_f32_16x16x32_bf16 v[0:3], v[170:173], v[206:209], 0
	v_mfma_f32_16x16x32_bf16 v[28:31], v[166:169], v[182:185], v[28:31]
	v_mfma_f32_16x16x32_bf16 v[24:27], v[174:177], v[182:185], v[24:27]
	v_mfma_f32_16x16x32_bf16 v[20:23], v[166:169], v[194:197], v[20:23]
	v_mfma_f32_16x16x32_bf16 v[16:19], v[174:177], v[194:197], v[16:19]
	v_mfma_f32_16x16x32_bf16 v[12:15], v[166:169], v[202:205], v[12:15]
	v_mfma_f32_16x16x32_bf16 v[8:11], v[174:177], v[202:205], v[8:11]
	v_mfma_f32_16x16x32_bf16 v[4:7], v[166:169], v[228:231], v[4:7]
	v_mfma_f32_16x16x32_bf16 v[0:3], v[174:177], v[228:231], v[0:3]
	s_barrier
	s_add_i32 s84, 0, 0x18000
	v_add_u32_e32 v140, s84, v146
	s_add_i32 s85, 0, 0x1c000
	ds_read_b128 v[142:145], v140
	ds_read_b128 v[150:153], v140 offset:1024
	ds_read_b128 v[154:157], v140 offset:2048
	ds_read_b128 v[158:161], v140 offset:3072
	v_add_u32_e32 v140, s85, v146
	ds_read_b128 v[162:165], v140
	ds_read_b128 v[166:169], v140 offset:1024
	ds_read_b128 v[170:173], v140 offset:2048
	ds_read_b128 v[174:177], v140 offset:3072
	s_add_u32 s64, s64, 0x40000
	s_addc_u32 s65, s65, 0
	s_mov_b32 m0, s21
	v_lshl_add_u64 v[234:235], s[64:65], 0, v[134:135]
	ds_read_b128 v[178:181], v148 offset:32768
	ds_read_b128 v[182:185], v148 offset:33792
	ds_read_b128 v[190:193], v148 offset:34816
	ds_read_b128 v[194:197], v148 offset:35840
	ds_read_b128 v[198:201], v148 offset:36864
	ds_read_b128 v[202:205], v148 offset:37888
	ds_read_b128 v[206:209], v148 offset:38912
	ds_read_b128 v[228:231], v148 offset:39936
	global_load_lds_dwordx4 v[234:235], off
	v_lshl_add_u64 v[234:235], s[64:65], 0, v[132:133]
	s_mov_b32 m0, s22
	s_nop 0
	global_load_lds_dwordx4 v[234:235], off
	s_waitcnt vmcnt(8)
	s_waitcnt lgkmcnt(0)
	s_barrier
	s_waitcnt lgkmcnt(0)
	v_mfma_f32_16x16x32_bf16 v[124:127], v[142:145], v[178:181], v[124:127]
	v_mfma_f32_16x16x32_bf16 v[120:123], v[154:157], v[178:181], v[120:123]
	v_mfma_f32_16x16x32_bf16 v[116:119], v[142:145], v[190:193], v[116:119]
	v_mfma_f32_16x16x32_bf16 v[112:115], v[154:157], v[190:193], v[112:115]
	v_mfma_f32_16x16x32_bf16 v[108:111], v[142:145], v[198:201], v[108:111]
	v_mfma_f32_16x16x32_bf16 v[104:107], v[154:157], v[198:201], v[104:107]
	v_mfma_f32_16x16x32_bf16 v[100:103], v[142:145], v[206:209], v[100:103]
	v_mfma_f32_16x16x32_bf16 v[96:99], v[154:157], v[206:209], v[96:99]
	v_mfma_f32_16x16x32_bf16 v[124:127], v[150:153], v[182:185], v[124:127]
	v_mfma_f32_16x16x32_bf16 v[120:123], v[158:161], v[182:185], v[120:123]
	v_mfma_f32_16x16x32_bf16 v[116:119], v[150:153], v[194:197], v[116:119]
	v_mfma_f32_16x16x32_bf16 v[112:115], v[158:161], v[194:197], v[112:115]
	v_mfma_f32_16x16x32_bf16 v[108:111], v[150:153], v[202:205], v[108:111]
	v_mfma_f32_16x16x32_bf16 v[104:107], v[158:161], v[202:205], v[104:107]
	v_mfma_f32_16x16x32_bf16 v[100:103], v[150:153], v[228:231], v[100:103]
	v_mfma_f32_16x16x32_bf16 v[96:99], v[158:161], v[228:231], v[96:99]
	v_mfma_f32_16x16x32_bf16 v[92:95], v[162:165], v[178:181], v[92:95]
	v_mfma_f32_16x16x32_bf16 v[88:91], v[170:173], v[178:181], v[88:91]
	v_mfma_f32_16x16x32_bf16 v[84:87], v[162:165], v[190:193], v[84:87]
	v_mfma_f32_16x16x32_bf16 v[80:83], v[170:173], v[190:193], v[80:83]
	v_mfma_f32_16x16x32_bf16 v[76:79], v[162:165], v[198:201], v[76:79]
	v_mfma_f32_16x16x32_bf16 v[72:75], v[170:173], v[198:201], v[72:75]
	v_mfma_f32_16x16x32_bf16 v[68:71], v[162:165], v[206:209], v[68:71]
	v_mfma_f32_16x16x32_bf16 v[64:67], v[170:173], v[206:209], v[64:67]
	v_mfma_f32_16x16x32_bf16 v[92:95], v[166:169], v[182:185], v[92:95]
	v_mfma_f32_16x16x32_bf16 v[88:91], v[174:177], v[182:185], v[88:91]
	v_mfma_f32_16x16x32_bf16 v[84:87], v[166:169], v[194:197], v[84:87]
	v_mfma_f32_16x16x32_bf16 v[80:83], v[174:177], v[194:197], v[80:83]
	v_mfma_f32_16x16x32_bf16 v[76:79], v[166:169], v[202:205], v[76:79]
	v_mfma_f32_16x16x32_bf16 v[72:75], v[174:177], v[202:205], v[72:75]
	v_mfma_f32_16x16x32_bf16 v[68:71], v[166:169], v[228:231], v[68:71]
	v_mfma_f32_16x16x32_bf16 v[64:67], v[174:177], v[228:231], v[64:67]
	s_barrier
; #define PG8_STAGE(bufoff, gbase, voff) do { _Pragma("unroll") for (int _i = 0; _i < 2; ++_i) \
;         __builtin_amdgcn_global_load_lds((const unsigned*)((const char*)(gbase) + (voff)[_i]), (PG8_LAS unsigned*)(lds + (bufoff) + ldsw + _i * 8192), 16, 0, 0); } while (0)
; #define PG8_LDA(dst, b, h) do { _Pragma("unroll") for (int m = 0; m < 4; ++m) _Pragma("unroll") for (int k = 0; k < 2; ++k) dst[m][k] = *(const PG8_LAS bf16x8*)(lds + PG8_SA(b, h) + aoff + m * 2048 + k * 1024); } while (0)
; #define PG8_MMA(ai, bj, At, Bt) do { __builtin_amdgcn_s_setprio(1); _Pragma("unroll") for (int m = 0; m < 4; ++m) _Pragma("unroll") for (int n = 0; n < 2; ++n) _Pragma("unroll") for (int k = 0; k < 2; ++k) \
;         acc[ai][bj][m][n] = __builtin_amdgcn_mfma_f32_16x16x32_bf16(Bt[n][k], At[m][k], acc[ai][bj][m][n], 0, 0, 0); __builtin_amdgcn_s_setprio(0); } while (0)
; #define PG8_WAIT_V(n) asm volatile("s_waitcnt vmcnt(" #n ")" ::: "memory")
; #define PG8_WAIT_L(n) asm volatile("s_waitcnt lgkmcnt(" #n ")" ::: "memory")
; #define PG8_BAR __builtin_amdgcn_s_barrier()
; #define PG8_SCHED __builtin_amdgcn_sched_barrier(0)
; template <class Epi, class Sched, bool ALIGN_EPI = false, bool SP2 = false>
; __device__ __forceinline__ void gemm_phase(PG8_LAS unsigned char* lds, const Gemm g, const Sched& S, const Epi& E) {
;     ...
;         for (int t = 0; t < nt; t += 2) {
;             const bool last = (t == nt - 2);
;     ...
;             PG8_LDA(At, 1, 1); PG8_STAGE(PG8_SB(1, 0), b3, voffB); PG8_STAGE(PG8_SB(1, 1), b3 + hstep, voffB); PG8_STAGE(PG8_SA(1, 0), a3, voffA);
;             PG8_WAIT_V(8); PG8_WAIT_L(0); PG8_BAR; PG8_MMA(1, 0, At, B0); PG8_MMA(1, 1, At, B1); PG8_BAR; PG8_SCHED;
	s_add_i32 s64, s84, s18
	v_lshl_add_u64 v[186:187], v[186:187], 0, s[90:91]
	s_mov_b32 m0, s64
	ds_read_b128 v[178:181], v148 offset:49152
	ds_read_b128 v[182:185], v148 offset:50176
	ds_read_b128 v[190:193], v148 offset:51200
	ds_read_b128 v[194:197], v148 offset:52224
	ds_read_b128 v[198:201], v148 offset:53248
	ds_read_b128 v[202:205], v148 offset:54272
	ds_read_b128 v[206:209], v148 offset:55296
	ds_read_b128 v[228:231], v148 offset:56320
	global_load_lds_dwordx4 v[186:187], off
	s_add_i32 m0, s64, 0x2000
	s_add_u32 s58, s58, 0x40080
	v_lshl_add_u64 v[186:187], v[188:189], 0, s[90:91]
	s_addc_u32 s59, s59, 0
	s_add_i32 s64, s85, s18
	global_load_lds_dwordx4 v[186:187], off
	v_lshl_add_u64 v[186:187], s[58:59], 0, v[128:129]
	s_mov_b32 m0, s64
	s_nop 0
	global_load_lds_dwordx4 v[186:187], off
	v_lshl_add_u64 v[186:187], s[58:59], 0, v[130:131]
	s_add_i32 m0, s64, 0x2000
	s_nop 0
	global_load_lds_dwordx4 v[186:187], off
	v_lshl_add_u64 v[186:187], v[210:211], 0, s[90:91]
	s_mov_b32 m0, s28
	s_nop 0
	global_load_lds_dwordx4 v[186:187], off
	v_lshl_add_u64 v[186:187], v[232:233], 0, s[90:91]
	s_mov_b32 m0, s29
	s_nop 0
	global_load_lds_dwordx4 v[186:187], off
	s_waitcnt vmcnt(8)
	s_waitcnt lgkmcnt(0)
	s_barrier
	s_waitcnt lgkmcnt(0)
	v_mfma_f32_16x16x32_bf16 v[60:63], v[142:145], v[178:181], v[60:63]
	v_mfma_f32_16x16x32_bf16 v[56:59], v[154:157], v[178:181], v[56:59]
	v_mfma_f32_16x16x32_bf16 v[52:55], v[142:145], v[190:193], v[52:55]
	v_mfma_f32_16x16x32_bf16 v[48:51], v[154:157], v[190:193], v[48:51]
	v_mfma_f32_16x16x32_bf16 v[44:47], v[142:145], v[198:201], v[44:47]
	v_mfma_f32_16x16x32_bf16 v[40:43], v[154:157], v[198:201], v[40:43]
	v_mfma_f32_16x16x32_bf16 v[36:39], v[142:145], v[206:209], v[36:39]
	v_mfma_f32_16x16x32_bf16 v[32:35], v[154:157], v[206:209], v[32:35]
	v_mfma_f32_16x16x32_bf16 v[60:63], v[150:153], v[182:185], v[60:63]
	v_mfma_f32_16x16x32_bf16 v[56:59], v[158:161], v[182:185], v[56:59]
	v_mfma_f32_16x16x32_bf16 v[52:55], v[150:153], v[194:197], v[52:55]
	v_mfma_f32_16x16x32_bf16 v[48:51], v[158:161], v[194:197], v[48:51]
	v_mfma_f32_16x16x32_bf16 v[44:47], v[150:153], v[202:205], v[44:47]
	v_mfma_f32_16x16x32_bf16 v[40:43], v[158:161], v[202:205], v[40:43]
	v_mfma_f32_16x16x32_bf16 v[36:39], v[150:153], v[228:231], v[36:39]
	v_mfma_f32_16x16x32_bf16 v[32:35], v[158:161], v[228:231], v[32:35]
	v_mfma_f32_16x16x32_bf16 v[28:31], v[162:165], v[178:181], v[28:31]
	v_mfma_f32_16x16x32_bf16 v[24:27], v[170:173], v[178:181], v[24:27]
	v_mfma_f32_16x16x32_bf16 v[20:23], v[162:165], v[190:193], v[20:23]
	v_mfma_f32_16x16x32_bf16 v[16:19], v[170:173], v[190:193], v[16:19]
	v_mfma_f32_16x16x32_bf16 v[12:15], v[162:165], v[198:201], v[12:15]
	v_mfma_f32_16x16x32_bf16 v[8:11], v[170:173], v[198:201], v[8:11]
	v_mfma_f32_16x16x32_bf16 v[4:7], v[162:165], v[206:209], v[4:7]
	v_mfma_f32_16x16x32_bf16 v[0:3], v[170:173], v[206:209], v[0:3]
	v_mfma_f32_16x16x32_bf16 v[28:31], v[166:169], v[182:185], v[28:31]
	v_mfma_f32_16x16x32_bf16 v[24:27], v[174:177], v[182:185], v[24:27]
	v_mfma_f32_16x16x32_bf16 v[20:23], v[166:169], v[194:197], v[20:23]
	v_mfma_f32_16x16x32_bf16 v[16:19], v[174:177], v[194:197], v[16:19]
	v_mfma_f32_16x16x32_bf16 v[12:15], v[166:169], v[202:205], v[12:15]
	v_mfma_f32_16x16x32_bf16 v[8:11], v[174:177], v[202:205], v[8:11]
	v_mfma_f32_16x16x32_bf16 v[4:7], v[166:169], v[228:231], v[4:7]
	v_mfma_f32_16x16x32_bf16 v[0:3], v[174:177], v[228:231], v[0:3]
	s_barrier
	s_add_i32 s94, s94, 2
	s_add_u32 s72, s72, 0x100
	s_addc_u32 s73, s73, 0
	s_add_u32 s92, s92, 0x100
	s_addc_u32 s93, s93, 0
	s_cmp_gt_u32 s94, 11
	s_cbranch_scc1 .Lklast_1
.LBB0_164:
	s_add_u32 s58, s72, 0xfffc0080
	s_addc_u32 s59, s73, -1
	s_add_i32 s84, 0, 0x10000
	s_cmp_eq_u32 s94, 12
	s_cselect_b32 s65, s36, s59
	s_cselect_b32 s64, s37, s58
	v_add_u32_e32 v140, s84, v146
	s_cselect_b32 s59, s51, s93
	s_cselect_b32 s58, s53, s92
	s_add_i32 s96, 0, 0x14000
	ds_read_b128 v[142:145], v140
	ds_read_b128 v[150:153], v140 offset:1024
	ds_read_b128 v[154:157], v140 offset:2048
	ds_read_b128 v[158:161], v140 offset:3072
	v_add_u32_e32 v140, s96, v146
	ds_read_b128 v[162:165], v140
	ds_read_b128 v[166:169], v140 offset:1024
	ds_read_b128 v[170:173], v140 offset:2048
	ds_read_b128 v[174:177], v140 offset:3072
	v_lshl_add_u64 v[186:187], s[72:73], 0, v[136:137]
	s_add_i32 m0, s19, 0xc000
	ds_read_b128 v[178:181], v148
	ds_read_b128 v[182:185], v148 offset:1024
	ds_read_b128 v[190:193], v148 offset:2048
	ds_read_b128 v[194:197], v148 offset:3072
	ds_read_b128 v[198:201], v148 offset:4096
	ds_read_b128 v[202:205], v148 offset:5120
	ds_read_b128 v[206:209], v148 offset:6144
	ds_read_b128 v[228:231], v148 offset:7168
	global_load_lds_dwordx4 v[186:187], off
	v_lshl_add_u64 v[186:187], s[72:73], 0, v[138:139]
	s_add_i32 m0, s19, 0xe000
	s_nop 0
	global_load_lds_dwordx4 v[186:187], off
	s_waitcnt vmcnt(8)
	s_waitcnt lgkmcnt(0)
	s_barrier
; #define PG8_STAGE(bufoff, gbase, voff) do { _Pragma("unroll") for (int _i = 0; _i < 2; ++_i) \
;         __builtin_amdgcn_global_load_lds((const unsigned*)((const char*)(gbase) + (voff)[_i]), (PG8_LAS unsigned*)(lds + (bufoff) + ldsw + _i * 8192), 16, 0, 0); } while (0)
; #define PG8_LDA(dst, b, h) do { _Pragma("unroll") for (int m = 0; m < 4; ++m) _Pragma("unroll") for (int k = 0; k < 2; ++k) dst[m][k] = *(const PG8_LAS bf16x8*)(lds + PG8_SA(b, h) + aoff + m * 2048 + k * 1024); } while (0)
; #define PG8_LDB(dst, b, h) do { _Pragma("unroll") for (int n = 0; n < 2; ++n) _Pragma("unroll") for (int k = 0; k < 2; ++k) dst[n][k] = *(const PG8_LAS bf16x8*)(lds + PG8_SB(b, h) + boff + n * 2048 + k * 1024); } while (0)
; #define PG8_MMA(ai, bj, At, Bt) do { __builtin_amdgcn_s_setprio(1); _Pragma("unroll") for (int m = 0; m < 4; ++m) _Pragma("unroll") for (int n = 0; n < 2; ++n) _Pragma("unroll") for (int k = 0; k < 2; ++k) \
;         acc[ai][bj][m][n] = __builtin_amdgcn_mfma_f32_16x16x32_bf16(Bt[n][k], At[m][k], acc[ai][bj][m][n], 0, 0, 0); __builtin_amdgcn_s_setprio(0); } while (0)
; #define PG8_WAIT_V(n) asm volatile("s_waitcnt vmcnt(" #n ")" ::: "memory")
; #define PG8_WAIT_L(n) asm volatile("s_waitcnt lgkmcnt(" #n ")" ::: "memory")
; #define PG8_BAR __builtin_amdgcn_s_barrier()
; #define PG8_SCHED __builtin_amdgcn_sched_barrier(0)
; template <class Epi, class Sched, bool ALIGN_EPI = false, bool SP2 = false>
; __device__ __forceinline__ void gemm_phase(PG8_LAS unsigned char* lds, const Gemm g, const Sched& S, const Epi& E) {
;     ...
;             PG8_WAIT_V(8); PG8_WAIT_L(0); PG8_BAR; PG8_MMA(0, 0, At, B0); PG8_MMA(0, 1, At, B1); PG8_BAR; PG8_SCHED;
;             PG8_LDA(At, 0, 1); PG8_STAGE(PG8_SB(0, 0), b2, voffB); PG8_STAGE(PG8_SB(0, 1), b2 + hstep, voffB); PG8_STAGE(PG8_SA(0, 0), a2, voffA);
;             PG8_WAIT_V(8); PG8_WAIT_L(0); PG8_BAR; PG8_MMA(1, 0, At, B0); PG8_MMA(1, 1, At, B1); PG8_BAR; PG8_SCHED;
;             PG8_LDB(B0, 1, 0); PG8_LDB(B1, 1, 1); PG8_SCHED; PG8_LDA(At, 1, 0); PG8_STAGE(PG8_SA(0, 1), a2 + hstep, voffA);
;             PG8_WAIT_V(8); PG8_WAIT_L(0); PG8_BAR; PG8_MMA(0, 0, At, B0); PG8_MMA(0, 1, At, B1); PG8_BAR; PG8_SCHED;
	s_waitcnt lgkmcnt(0)
	v_mfma_f32_16x16x32_bf16 v[124:127], v[142:145], v[178:181], v[124:127]
	v_mfma_f32_16x16x32_bf16 v[120:123], v[154:157], v[178:181], v[120:123]
	v_mfma_f32_16x16x32_bf16 v[116:119], v[142:145], v[190:193], v[116:119]
	v_mfma_f32_16x16x32_bf16 v[112:115], v[154:157], v[190:193], v[112:115]
	v_mfma_f32_16x16x32_bf16 v[108:111], v[142:145], v[198:201], v[108:111]
	v_mfma_f32_16x16x32_bf16 v[104:107], v[154:157], v[198:201], v[104:107]
	v_mfma_f32_16x16x32_bf16 v[100:103], v[142:145], v[206:209], v[100:103]
	v_mfma_f32_16x16x32_bf16 v[96:99], v[154:157], v[206:209], v[96:99]
	v_mfma_f32_16x16x32_bf16 v[124:127], v[150:153], v[182:185], v[124:127]
	v_mfma_f32_16x16x32_bf16 v[120:123], v[158:161], v[182:185], v[120:123]
	v_mfma_f32_16x16x32_bf16 v[116:119], v[150:153], v[194:197], v[116:119]
	v_mfma_f32_16x16x32_bf16 v[112:115], v[158:161], v[194:197], v[112:115]
	v_mfma_f32_16x16x32_bf16 v[108:111], v[150:153], v[202:205], v[108:111]
	v_mfma_f32_16x16x32_bf16 v[104:107], v[158:161], v[202:205], v[104:107]
	v_mfma_f32_16x16x32_bf16 v[100:103], v[150:153], v[228:231], v[100:103]
	v_mfma_f32_16x16x32_bf16 v[96:99], v[158:161], v[228:231], v[96:99]
	v_mfma_f32_16x16x32_bf16 v[92:95], v[162:165], v[178:181], v[92:95]
	v_mfma_f32_16x16x32_bf16 v[88:91], v[170:173], v[178:181], v[88:91]
	v_mfma_f32_16x16x32_bf16 v[84:87], v[162:165], v[190:193], v[84:87]
	v_mfma_f32_16x16x32_bf16 v[80:83], v[170:173], v[190:193], v[80:83]
	v_mfma_f32_16x16x32_bf16 v[76:79], v[162:165], v[198:201], v[76:79]
	v_mfma_f32_16x16x32_bf16 v[72:75], v[170:173], v[198:201], v[72:75]
	v_mfma_f32_16x16x32_bf16 v[68:71], v[162:165], v[206:209], v[68:71]
	v_mfma_f32_16x16x32_bf16 v[64:67], v[170:173], v[206:209], v[64:67]
	v_mfma_f32_16x16x32_bf16 v[92:95], v[166:169], v[182:185], v[92:95]
	v_mfma_f32_16x16x32_bf16 v[88:91], v[174:177], v[182:185], v[88:91]
	v_mfma_f32_16x16x32_bf16 v[84:87], v[166:169], v[194:197], v[84:87]
	v_mfma_f32_16x16x32_bf16 v[80:83], v[174:177], v[194:197], v[80:83]
	v_mfma_f32_16x16x32_bf16 v[76:79], v[166:169], v[202:205], v[76:79]
	v_mfma_f32_16x16x32_bf16 v[72:75], v[174:177], v[202:205], v[72:75]
	v_mfma_f32_16x16x32_bf16 v[68:71], v[166:169], v[228:231], v[68:71]
	v_mfma_f32_16x16x32_bf16 v[64:67], v[174:177], v[228:231], v[64:67]
	s_barrier
	s_add_i32 s84, s84, s18
	v_lshl_add_u64 v[186:187], s[58:59], 0, v[128:129]
	s_mov_b32 m0, s84
	ds_read_b128 v[178:181], v148 offset:16384
	ds_read_b128 v[182:185], v148 offset:17408
	ds_read_b128 v[190:193], v148 offset:18432
	ds_read_b128 v[194:197], v148 offset:19456
	ds_read_b128 v[198:201], v148 offset:20480
	ds_read_b128 v[202:205], v148 offset:21504
	ds_read_b128 v[206:209], v148 offset:22528
	ds_read_b128 v[228:231], v148 offset:23552
	global_load_lds_dwordx4 v[186:187], off
	s_add_i32 m0, s84, 0x2000
	s_add_u32 s84, s58, 0x40000
	v_lshl_add_u64 v[188:189], s[58:59], 0, v[130:131]
	s_addc_u32 s85, s59, 0
	s_add_i32 s96, s96, s18
	global_load_lds_dwordx4 v[188:189], off
	v_lshl_add_u64 v[210:211], s[84:85], 0, v[128:129]
	s_mov_b32 m0, s96
	v_lshl_add_u64 v[232:233], s[64:65], 0, v[132:133]
	global_load_lds_dwordx4 v[210:211], off
	v_lshl_add_u64 v[210:211], s[84:85], 0, v[130:131]
	s_add_i32 m0, s96, 0x2000
	s_nop 0
	global_load_lds_dwordx4 v[210:211], off
	v_lshl_add_u64 v[210:211], s[64:65], 0, v[134:135]
	s_mov_b32 m0, s19
	s_nop 0
	global_load_lds_dwordx4 v[210:211], off
	s_mov_b32 m0, s20
	s_nop 0
	global_load_lds_dwordx4 v[232:233], off
	s_waitcnt vmcnt(8)
	s_waitcnt lgkmcnt(0)
	s_barrier
	s_waitcnt lgkmcnt(0)
	v_mfma_f32_16x16x32_bf16 v[60:63], v[142:145], v[178:181], v[60:63]
	v_mfma_f32_16x16x32_bf16 v[56:59], v[154:157], v[178:181], v[56:59]
	v_mfma_f32_16x16x32_bf16 v[52:55], v[142:145], v[190:193], v[52:55]
	v_mfma_f32_16x16x32_bf16 v[48:51], v[154:157], v[190:193], v[48:51]
	v_mfma_f32_16x16x32_bf16 v[44:47], v[142:145], v[198:201], v[44:47]
	v_mfma_f32_16x16x32_bf16 v[40:43], v[154:157], v[198:201], v[40:43]
	v_mfma_f32_16x16x32_bf16 v[36:39], v[142:145], v[206:209], v[36:39]
	v_mfma_f32_16x16x32_bf16 v[32:35], v[154:157], v[206:209], v[32:35]
	v_mfma_f32_16x16x32_bf16 v[60:63], v[150:153], v[182:185], v[60:63]
	v_mfma_f32_16x16x32_bf16 v[56:59], v[158:161], v[182:185], v[56:59]
	v_mfma_f32_16x16x32_bf16 v[52:55], v[150:153], v[194:197], v[52:55]
	v_mfma_f32_16x16x32_bf16 v[48:51], v[158:161], v[194:197], v[48:51]
	v_mfma_f32_16x16x32_bf16 v[44:47], v[150:153], v[202:205], v[44:47]
	v_mfma_f32_16x16x32_bf16 v[40:43], v[158:161], v[202:205], v[40:43]
	v_mfma_f32_16x16x32_bf16 v[36:39], v[150:153], v[228:231], v[36:39]
	v_mfma_f32_16x16x32_bf16 v[32:35], v[158:161], v[228:231], v[32:35]
	v_mfma_f32_16x16x32_bf16 v[28:31], v[162:165], v[178:181], v[28:31]
	v_mfma_f32_16x16x32_bf16 v[24:27], v[170:173], v[178:181], v[24:27]
	v_mfma_f32_16x16x32_bf16 v[20:23], v[162:165], v[190:193], v[20:23]
	v_mfma_f32_16x16x32_bf16 v[16:19], v[170:173], v[190:193], v[16:19]
	v_mfma_f32_16x16x32_bf16 v[12:15], v[162:165], v[198:201], v[12:15]
	v_mfma_f32_16x16x32_bf16 v[8:11], v[170:173], v[198:201], v[8:11]
	v_mfma_f32_16x16x32_bf16 v[4:7], v[162:165], v[206:209], v[4:7]
	v_mfma_f32_16x16x32_bf16 v[0:3], v[170:173], v[206:209], v[0:3]
	v_mfma_f32_16x16x32_bf16 v[28:31], v[166:169], v[182:185], v[28:31]
	v_mfma_f32_16x16x32_bf16 v[24:27], v[174:177], v[182:185], v[24:27]
	v_mfma_f32_16x16x32_bf16 v[20:23], v[166:169], v[194:197], v[20:23]
	v_mfma_f32_16x16x32_bf16 v[16:19], v[174:177], v[194:197], v[16:19]
	v_mfma_f32_16x16x32_bf16 v[12:15], v[166:169], v[202:205], v[12:15]
	v_mfma_f32_16x16x32_bf16 v[8:11], v[174:177], v[202:205], v[8:11]
	v_mfma_f32_16x16x32_bf16 v[4:7], v[166:169], v[228:231], v[4:7]
	v_mfma_f32_16x16x32_bf16 v[0:3], v[174:177], v[228:231], v[0:3]
	s_barrier
; #define PG8_STAGE(bufoff, gbase, voff) do { _Pragma("unroll") for (int _i = 0; _i < 2; ++_i) \
;         __builtin_amdgcn_global_load_lds((const unsigned*)((const char*)(gbase) + (voff)[_i]), (PG8_LAS unsigned*)(lds + (bufoff) + ldsw + _i * 8192), 16, 0, 0); } while (0)
; #define PG8_LDA(dst, b, h) do { _Pragma("unroll") for (int m = 0; m < 4; ++m) _Pragma("unroll") for (int k = 0; k < 2; ++k) dst[m][k] = *(const PG8_LAS bf16x8*)(lds + PG8_SA(b, h) + aoff + m * 2048 + k * 1024); } while (0)
; #define PG8_LDB(dst, b, h) do { _Pragma("unroll") for (int n = 0; n < 2; ++n) _Pragma("unroll") for (int k = 0; k < 2; ++k) dst[n][k] = *(const PG8_LAS bf16x8*)(lds + PG8_SB(b, h) + boff + n * 2048 + k * 1024); } while (0)
; #define PG8_MMA(ai, bj, At, Bt) do { __builtin_amdgcn_s_setprio(1); _Pragma("unroll") for (int m = 0; m < 4; ++m) _Pragma("unroll") for (int n = 0; n < 2; ++n) _Pragma("unroll") for (int k = 0; k < 2; ++k) \
;         acc[ai][bj][m][n] = __builtin_amdgcn_mfma_f32_16x16x32_bf16(Bt[n][k], At[m][k], acc[ai][bj][m][n], 0, 0, 0); __builtin_amdgcn_s_setprio(0); } while (0)
; #define PG8_WAIT_V(n) asm volatile("s_waitcnt vmcnt(" #n ")" ::: "memory")
; #define PG8_WAIT_L(n) asm volatile("s_waitcnt lgkmcnt(" #n ")" ::: "memory")
; #define PG8_BAR __builtin_amdgcn_s_barrier()
; #define PG8_SCHED __builtin_amdgcn_sched_barrier(0)
; template <class Epi, class Sched, bool ALIGN_EPI = false, bool SP2 = false>
; __device__ __forceinline__ void gemm_phase(PG8_LAS unsigned char* lds, const Gemm g, const Sched& S, const Epi& E) {
;     ...
;         for (int t = 0; t < nt; t += 2) {
;             const bool last = (t == nt - 2);
;     ...
;             PG8_LDB(B0, 1, 0); PG8_LDB(B1, 1, 1); PG8_SCHED; PG8_LDA(At, 1, 0); PG8_STAGE(PG8_SA(0, 1), a2 + hstep, voffA);
;             PG8_WAIT_V(8); PG8_WAIT_L(0); PG8_BAR; PG8_MMA(0, 0, At, B0); PG8_MMA(0, 1, At, B1); PG8_BAR; PG8_SCHED;
;             PG8_LDA(At, 1, 1); PG8_STAGE(PG8_SB(1, 0), b3, voffB); PG8_STAGE(PG8_SB(1, 1), b3 + hstep, voffB); PG8_STAGE(PG8_SA(1, 0), a3, voffA);
;             PG8_WAIT_V(8); PG8_WAIT_L(0); PG8_BAR; PG8_MMA(1, 0, At, B0); PG8_MMA(1, 1, At, B1); PG8_BAR; PG8_SCHED;
	s_add_i32 s84, 0, 0x18000
	v_add_u32_e32 v140, s84, v146
	s_add_i32 s85, 0, 0x1c000
	ds_read_b128 v[142:145], v140
	ds_read_b128 v[150:153], v140 offset:1024
	ds_read_b128 v[154:157], v140 offset:2048
	ds_read_b128 v[158:161], v140 offset:3072
	v_add_u32_e32 v140, s85, v146
	ds_read_b128 v[162:165], v140
	ds_read_b128 v[166:169], v140 offset:1024
	ds_read_b128 v[170:173], v140 offset:2048
	ds_read_b128 v[174:177], v140 offset:3072
	s_add_u32 s64, s64, 0x40000
	s_addc_u32 s65, s65, 0
	s_mov_b32 m0, s21
	v_lshl_add_u64 v[234:235], s[64:65], 0, v[134:135]
	ds_read_b128 v[178:181], v148 offset:32768
	ds_read_b128 v[182:185], v148 offset:33792
	ds_read_b128 v[190:193], v148 offset:34816
	ds_read_b128 v[194:197], v148 offset:35840
	ds_read_b128 v[198:201], v148 offset:36864
	ds_read_b128 v[202:205], v148 offset:37888
	ds_read_b128 v[206:209], v148 offset:38912
	ds_read_b128 v[228:231], v148 offset:39936
	global_load_lds_dwordx4 v[234:235], off
	v_lshl_add_u64 v[234:235], s[64:65], 0, v[132:133]
	s_mov_b32 m0, s22
	s_nop 0
	global_load_lds_dwordx4 v[234:235], off
	s_waitcnt vmcnt(8)
	s_waitcnt lgkmcnt(0)
	s_barrier
	s_waitcnt lgkmcnt(0)
	v_mfma_f32_16x16x32_bf16 v[124:127], v[142:145], v[178:181], v[124:127]
	v_mfma_f32_16x16x32_bf16 v[120:123], v[154:157], v[178:181], v[120:123]
	v_mfma_f32_16x16x32_bf16 v[116:119], v[142:145], v[190:193], v[116:119]
	v_mfma_f32_16x16x32_bf16 v[112:115], v[154:157], v[190:193], v[112:115]
	v_mfma_f32_16x16x32_bf16 v[108:111], v[142:145], v[198:201], v[108:111]
	v_mfma_f32_16x16x32_bf16 v[104:107], v[154:157], v[198:201], v[104:107]
	v_mfma_f32_16x16x32_bf16 v[100:103], v[142:145], v[206:209], v[100:103]
	v_mfma_f32_16x16x32_bf16 v[96:99], v[154:157], v[206:209], v[96:99]
	v_mfma_f32_16x16x32_bf16 v[124:127], v[150:153], v[182:185], v[124:127]
	v_mfma_f32_16x16x32_bf16 v[120:123], v[158:161], v[182:185], v[120:123]
	v_mfma_f32_16x16x32_bf16 v[116:119], v[150:153], v[194:197], v[116:119]
	v_mfma_f32_16x16x32_bf16 v[112:115], v[158:161], v[194:197], v[112:115]
	v_mfma_f32_16x16x32_bf16 v[108:111], v[150:153], v[202:205], v[108:111]
	v_mfma_f32_16x16x32_bf16 v[104:107], v[158:161], v[202:205], v[104:107]
	v_mfma_f32_16x16x32_bf16 v[100:103], v[150:153], v[228:231], v[100:103]
	v_mfma_f32_16x16x32_bf16 v[96:99], v[158:161], v[228:231], v[96:99]
	v_mfma_f32_16x16x32_bf16 v[92:95], v[162:165], v[178:181], v[92:95]
	v_mfma_f32_16x16x32_bf16 v[88:91], v[170:173], v[178:181], v[88:91]
	v_mfma_f32_16x16x32_bf16 v[84:87], v[162:165], v[190:193], v[84:87]
	v_mfma_f32_16x16x32_bf16 v[80:83], v[170:173], v[190:193], v[80:83]
	v_mfma_f32_16x16x32_bf16 v[76:79], v[162:165], v[198:201], v[76:79]
	v_mfma_f32_16x16x32_bf16 v[72:75], v[170:173], v[198:201], v[72:75]
	v_mfma_f32_16x16x32_bf16 v[68:71], v[162:165], v[206:209], v[68:71]
	v_mfma_f32_16x16x32_bf16 v[64:67], v[170:173], v[206:209], v[64:67]
	v_mfma_f32_16x16x32_bf16 v[92:95], v[166:169], v[182:185], v[92:95]
	v_mfma_f32_16x16x32_bf16 v[88:91], v[174:177], v[182:185], v[88:91]
	v_mfma_f32_16x16x32_bf16 v[84:87], v[166:169], v[194:197], v[84:87]
	v_mfma_f32_16x16x32_bf16 v[80:83], v[174:177], v[194:197], v[80:83]
	v_mfma_f32_16x16x32_bf16 v[76:79], v[166:169], v[202:205], v[76:79]
	v_mfma_f32_16x16x32_bf16 v[72:75], v[174:177], v[202:205], v[72:75]
	v_mfma_f32_16x16x32_bf16 v[68:71], v[166:169], v[228:231], v[68:71]
	v_mfma_f32_16x16x32_bf16 v[64:67], v[174:177], v[228:231], v[64:67]
	s_barrier
	s_add_i32 s64, s84, s18
	v_lshl_add_u64 v[186:187], v[186:187], 0, s[90:91]
	s_mov_b32 m0, s64
	ds_read_b128 v[178:181], v148 offset:49152
	ds_read_b128 v[182:185], v148 offset:50176
	ds_read_b128 v[190:193], v148 offset:51200
	ds_read_b128 v[194:197], v148 offset:52224
	ds_read_b128 v[198:201], v148 offset:53248
	ds_read_b128 v[202:205], v148 offset:54272
	ds_read_b128 v[206:209], v148 offset:55296
	ds_read_b128 v[228:231], v148 offset:56320
	global_load_lds_dwordx4 v[186:187], off
	s_add_i32 m0, s64, 0x2000
	s_add_u32 s58, s58, 0x40080
	v_lshl_add_u64 v[186:187], v[188:189], 0, s[90:91]
	s_addc_u32 s59, s59, 0
	s_add_i32 s64, s85, s18
	global_load_lds_dwordx4 v[186:187], off
	v_lshl_add_u64 v[186:187], s[58:59], 0, v[128:129]
	s_mov_b32 m0, s64
	s_nop 0
	global_load_lds_dwordx4 v[186:187], off
	v_lshl_add_u64 v[186:187], s[58:59], 0, v[130:131]
	s_add_i32 m0, s64, 0x2000
	s_nop 0
	global_load_lds_dwordx4 v[186:187], off
	v_lshl_add_u64 v[186:187], v[210:211], 0, s[90:91]
	s_mov_b32 m0, s28
	s_nop 0
	global_load_lds_dwordx4 v[186:187], off
	v_lshl_add_u64 v[186:187], v[232:233], 0, s[90:91]
	s_mov_b32 m0, s29
	s_nop 0
	global_load_lds_dwordx4 v[186:187], off
	s_waitcnt vmcnt(8)
	s_waitcnt lgkmcnt(0)
	s_barrier
	s_waitcnt lgkmcnt(0)
	v_mfma_f32_16x16x32_bf16 v[60:63], v[142:145], v[178:181], v[60:63]
	v_mfma_f32_16x16x32_bf16 v[56:59], v[154:157], v[178:181], v[56:59]
	v_mfma_f32_16x16x32_bf16 v[52:55], v[142:145], v[190:193], v[52:55]
	v_mfma_f32_16x16x32_bf16 v[48:51], v[154:157], v[190:193], v[48:51]
	v_mfma_f32_16x16x32_bf16 v[44:47], v[142:145], v[198:201], v[44:47]
	v_mfma_f32_16x16x32_bf16 v[40:43], v[154:157], v[198:201], v[40:43]
	v_mfma_f32_16x16x32_bf16 v[36:39], v[142:145], v[206:209], v[36:39]
	v_mfma_f32_16x16x32_bf16 v[32:35], v[154:157], v[206:209], v[32:35]
	v_mfma_f32_16x16x32_bf16 v[60:63], v[150:153], v[182:185], v[60:63]
	v_mfma_f32_16x16x32_bf16 v[56:59], v[158:161], v[182:185], v[56:59]
	v_mfma_f32_16x16x32_bf16 v[52:55], v[150:153], v[194:197], v[52:55]
	v_mfma_f32_16x16x32_bf16 v[48:51], v[158:161], v[194:197], v[48:51]
	v_mfma_f32_16x16x32_bf16 v[44:47], v[150:153], v[202:205], v[44:47]
	v_mfma_f32_16x16x32_bf16 v[40:43], v[158:161], v[202:205], v[40:43]
	v_mfma_f32_16x16x32_bf16 v[36:39], v[150:153], v[228:231], v[36:39]
	v_mfma_f32_16x16x32_bf16 v[32:35], v[158:161], v[228:231], v[32:35]
	v_mfma_f32_16x16x32_bf16 v[28:31], v[162:165], v[178:181], v[28:31]
	v_mfma_f32_16x16x32_bf16 v[24:27], v[170:173], v[178:181], v[24:27]
	v_mfma_f32_16x16x32_bf16 v[20:23], v[162:165], v[190:193], v[20:23]
	v_mfma_f32_16x16x32_bf16 v[16:19], v[170:173], v[190:193], v[16:19]
	v_mfma_f32_16x16x32_bf16 v[12:15], v[162:165], v[198:201], v[12:15]
	v_mfma_f32_16x16x32_bf16 v[8:11], v[170:173], v[198:201], v[8:11]
	v_mfma_f32_16x16x32_bf16 v[4:7], v[162:165], v[206:209], v[4:7]
	v_mfma_f32_16x16x32_bf16 v[0:3], v[170:173], v[206:209], v[0:3]
	v_mfma_f32_16x16x32_bf16 v[28:31], v[166:169], v[182:185], v[28:31]
	v_mfma_f32_16x16x32_bf16 v[24:27], v[174:177], v[182:185], v[24:27]
	v_mfma_f32_16x16x32_bf16 v[20:23], v[166:169], v[194:197], v[20:23]
	v_mfma_f32_16x16x32_bf16 v[16:19], v[174:177], v[194:197], v[16:19]
	v_mfma_f32_16x16x32_bf16 v[12:15], v[166:169], v[202:205], v[12:15]
	v_mfma_f32_16x16x32_bf16 v[8:11], v[174:177], v[202:205], v[8:11]
	v_mfma_f32_16x16x32_bf16 v[4:7], v[166:169], v[228:231], v[4:7]
	v_mfma_f32_16x16x32_bf16 v[0:3], v[174:177], v[228:231], v[0:3]
	s_barrier
	s_add_i32 s94, s94, 2
	s_add_u32 s72, s72, 0x100
	s_addc_u32 s73, s73, 0
	s_add_u32 s92, s92, 0x100
	s_addc_u32 s93, s93, 0
	s_cmp_gt_u32 s94, 11
	s_cbranch_scc0 .LBB0_164
; #define PG8_STAGE(bufoff, gbase, voff) do { _Pragma("unroll") for (int _i = 0; _i < 2; ++_i) \
;         __builtin_amdgcn_global_load_lds((const unsigned*)((const char*)(gbase) + (voff)[_i]), (PG8_LAS unsigned*)(lds + (bufoff) + ldsw + _i * 8192), 16, 0, 0); } while (0)
; #define PG8_LDA(dst, b, h) do { _Pragma("unroll") for (int m = 0; m < 4; ++m) _Pragma("unroll") for (int k = 0; k < 2; ++k) dst[m][k] = *(const PG8_LAS bf16x8*)(lds + PG8_SA(b, h) + aoff + m * 2048 + k * 1024); } while (0)
; #define PG8_LDB(dst, b, h) do { _Pragma("unroll") for (int n = 0; n < 2; ++n) _Pragma("unroll") for (int k = 0; k < 2; ++k) dst[n][k] = *(const PG8_LAS bf16x8*)(lds + PG8_SB(b, h) + boff + n * 2048 + k * 1024); } while (0)
; #define PG8_MMA(ai, bj, At, Bt) do { __builtin_amdgcn_s_setprio(1); _Pragma("unroll") for (int m = 0; m < 4; ++m) _Pragma("unroll") for (int n = 0; n < 2; ++n) _Pragma("unroll") for (int k = 0; k < 2; ++k) \
;         acc[ai][bj][m][n] = __builtin_amdgcn_mfma_f32_16x16x32_bf16(Bt[n][k], At[m][k], acc[ai][bj][m][n], 0, 0, 0); __builtin_amdgcn_s_setprio(0); } while (0)
; #define PG8_WAIT_V(n) asm volatile("s_waitcnt vmcnt(" #n ")" ::: "memory")
; #define PG8_WAIT_L(n) asm volatile("s_waitcnt lgkmcnt(" #n ")" ::: "memory")
; #define PG8_BAR __builtin_amdgcn_s_barrier()
; #define PG8_SCHED __builtin_amdgcn_sched_barrier(0)
; template <class Epi, class Sched, bool ALIGN_EPI = false, bool SP2 = false>
; __device__ __forceinline__ void gemm_phase(PG8_LAS unsigned char* lds, const Gemm g, const Sched& S, const Epi& E) {
;     ...
;             if constexpr (SP2) {
;             PG8_LDB(B0, 0, 0); PG8_LDB(B1, 0, 1); PG8_SCHED; PG8_LDA(At, 0, 0); PG8_STAGE(PG8_SA(1, 1), a1 + hstep, voffA);
;             PG8_WAIT_V(8); PG8_WAIT_L(0); PG8_BAR; PG8_MMA(0, 0, At, B0); PG8_MMA(0, 1, At, B1); PG8_BAR; PG8_SCHED;
;             PG8_LDA(At, 0, 1); PG8_STAGE(PG8_SB(0, 0), b2, voffB); PG8_STAGE(PG8_SB(0, 1), b2 + hstep, voffB); PG8_STAGE(PG8_SA(0, 0), a2, voffA);
.Lklast_1:
	s_add_u32 s58, s72, 0xfffc0080
	s_addc_u32 s59, s73, -1
	s_add_i32 s84, 0, 0x10000
	s_cmp_eq_u32 s94, 12
	s_cselect_b32 s65, s36, s59
	s_cselect_b32 s64, s37, s58
	v_add_u32_e32 v140, s84, v146
	s_cselect_b32 s59, s51, s93
	s_cselect_b32 s58, s53, s92
	s_add_i32 s96, 0, 0x14000
	ds_read_b128 v[142:145], v140
	ds_read_b128 v[150:153], v140 offset:1024
	ds_read_b128 v[154:157], v140 offset:2048
	ds_read_b128 v[158:161], v140 offset:3072
	v_add_u32_e32 v140, s96, v146
	ds_read_b128 v[162:165], v140
	ds_read_b128 v[166:169], v140 offset:1024
	ds_read_b128 v[170:173], v140 offset:2048
	ds_read_b128 v[174:177], v140 offset:3072
	v_lshl_add_u64 v[186:187], s[72:73], 0, v[136:137]
	s_add_i32 m0, s19, 0xc000
	ds_read_b128 v[178:181], v148
	ds_read_b128 v[182:185], v148 offset:1024
	ds_read_b128 v[190:193], v148 offset:2048
	ds_read_b128 v[194:197], v148 offset:3072
	ds_read_b128 v[198:201], v148 offset:4096
	ds_read_b128 v[202:205], v148 offset:5120
	ds_read_b128 v[206:209], v148 offset:6144
	ds_read_b128 v[228:231], v148 offset:7168
	global_load_lds_dwordx4 v[186:187], off
	v_lshl_add_u64 v[186:187], s[72:73], 0, v[138:139]
	s_add_i32 m0, s19, 0xe000
	s_nop 0
	global_load_lds_dwordx4 v[186:187], off
	s_waitcnt vmcnt(8)
	s_waitcnt lgkmcnt(0)
	s_barrier
	s_waitcnt lgkmcnt(0)
	v_mfma_f32_16x16x32_bf16 v[124:127], v[142:145], v[178:181], v[124:127]
	v_mfma_f32_16x16x32_bf16 v[120:123], v[154:157], v[178:181], v[120:123]
	v_mfma_f32_16x16x32_bf16 v[116:119], v[142:145], v[190:193], v[116:119]
	v_mfma_f32_16x16x32_bf16 v[112:115], v[154:157], v[190:193], v[112:115]
	v_mfma_f32_16x16x32_bf16 v[108:111], v[142:145], v[198:201], v[108:111]
	v_mfma_f32_16x16x32_bf16 v[104:107], v[154:157], v[198:201], v[104:107]
	v_mfma_f32_16x16x32_bf16 v[100:103], v[142:145], v[206:209], v[100:103]
	v_mfma_f32_16x16x32_bf16 v[96:99], v[154:157], v[206:209], v[96:99]
	v_mfma_f32_16x16x32_bf16 v[124:127], v[150:153], v[182:185], v[124:127]
	v_mfma_f32_16x16x32_bf16 v[120:123], v[158:161], v[182:185], v[120:123]
	v_mfma_f32_16x16x32_bf16 v[116:119], v[150:153], v[194:197], v[116:119]
	v_mfma_f32_16x16x32_bf16 v[112:115], v[158:161], v[194:197], v[112:115]
	v_mfma_f32_16x16x32_bf16 v[108:111], v[150:153], v[202:205], v[108:111]
	v_mfma_f32_16x16x32_bf16 v[104:107], v[158:161], v[202:205], v[104:107]
	v_mfma_f32_16x16x32_bf16 v[100:103], v[150:153], v[228:231], v[100:103]
	v_mfma_f32_16x16x32_bf16 v[96:99], v[158:161], v[228:231], v[96:99]
	v_mfma_f32_16x16x32_bf16 v[92:95], v[162:165], v[178:181], v[92:95]
	v_mfma_f32_16x16x32_bf16 v[88:91], v[170:173], v[178:181], v[88:91]
	v_mfma_f32_16x16x32_bf16 v[84:87], v[162:165], v[190:193], v[84:87]
	v_mfma_f32_16x16x32_bf16 v[80:83], v[170:173], v[190:193], v[80:83]
	v_mfma_f32_16x16x32_bf16 v[76:79], v[162:165], v[198:201], v[76:79]
	v_mfma_f32_16x16x32_bf16 v[72:75], v[170:173], v[198:201], v[72:75]
	v_mfma_f32_16x16x32_bf16 v[68:71], v[162:165], v[206:209], v[68:71]
	v_mfma_f32_16x16x32_bf16 v[64:67], v[170:173], v[206:209], v[64:67]
	v_mfma_f32_16x16x32_bf16 v[92:95], v[166:169], v[182:185], v[92:95]
	v_mfma_f32_16x16x32_bf16 v[88:91], v[174:177], v[182:185], v[88:91]
	v_mfma_f32_16x16x32_bf16 v[84:87], v[166:169], v[194:197], v[84:87]
	v_mfma_f32_16x16x32_bf16 v[80:83], v[174:177], v[194:197], v[80:83]
	v_mfma_f32_16x16x32_bf16 v[76:79], v[166:169], v[202:205], v[76:79]
	v_mfma_f32_16x16x32_bf16 v[72:75], v[174:177], v[202:205], v[72:75]
	v_mfma_f32_16x16x32_bf16 v[68:71], v[166:169], v[228:231], v[68:71]
	v_mfma_f32_16x16x32_bf16 v[64:67], v[174:177], v[228:231], v[64:67]
	s_barrier
	s_add_i32 s84, s84, s18
	v_lshl_add_u64 v[186:187], s[58:59], 0, v[128:129]
	s_mov_b32 m0, s84
	ds_read_b128 v[178:181], v148 offset:16384
	ds_read_b128 v[182:185], v148 offset:17408
	ds_read_b128 v[190:193], v148 offset:18432
	ds_read_b128 v[194:197], v148 offset:19456
	ds_read_b128 v[198:201], v148 offset:20480
	ds_read_b128 v[202:205], v148 offset:21504
	ds_read_b128 v[206:209], v148 offset:22528
	ds_read_b128 v[228:231], v148 offset:23552
	global_load_lds_dwordx4 v[186:187], off
	s_add_i32 m0, s84, 0x2000
	s_add_u32 s84, s58, 0x40000
	v_lshl_add_u64 v[188:189], s[58:59], 0, v[130:131]
	s_addc_u32 s85, s59, 0
	s_add_i32 s96, s96, s18
	global_load_lds_dwordx4 v[188:189], off
	v_lshl_add_u64 v[210:211], s[84:85], 0, v[128:129]
	s_mov_b32 m0, s96
	v_lshl_add_u64 v[232:233], s[64:65], 0, v[132:133]
	global_load_lds_dwordx4 v[210:211], off
	v_lshl_add_u64 v[210:211], s[84:85], 0, v[130:131]
	s_add_i32 m0, s96, 0x2000
	s_nop 0
	global_load_lds_dwordx4 v[210:211], off
	v_lshl_add_u64 v[210:211], s[64:65], 0, v[134:135]
	s_mov_b32 m0, s19
	s_nop 0
	global_load_lds_dwordx4 v[210:211], off
	s_mov_b32 m0, s20
	s_nop 0
	global_load_lds_dwordx4 v[232:233], off
	s_waitcnt vmcnt(8)
	s_waitcnt lgkmcnt(0)
	s_barrier
; #define PG8_STAGE(bufoff, gbase, voff) do { _Pragma("unroll") for (int _i = 0; _i < 2; ++_i) \
;         __builtin_amdgcn_global_load_lds((const unsigned*)((const char*)(gbase) + (voff)[_i]), (PG8_LAS unsigned*)(lds + (bufoff) + ldsw + _i * 8192), 16, 0, 0); } while (0)
; #define PG8_LDA(dst, b, h) do { _Pragma("unroll") for (int m = 0; m < 4; ++m) _Pragma("unroll") for (int k = 0; k < 2; ++k) dst[m][k] = *(const PG8_LAS bf16x8*)(lds + PG8_SA(b, h) + aoff + m * 2048 + k * 1024); } while (0)
; #define PG8_LDB(dst, b, h) do { _Pragma("unroll") for (int n = 0; n < 2; ++n) _Pragma("unroll") for (int k = 0; k < 2; ++k) dst[n][k] = *(const PG8_LAS bf16x8*)(lds + PG8_SB(b, h) + boff + n * 2048 + k * 1024); } while (0)
; #define PG8_MMA(ai, bj, At, Bt) do { __builtin_amdgcn_s_setprio(1); _Pragma("unroll") for (int m = 0; m < 4; ++m) _Pragma("unroll") for (int n = 0; n < 2; ++n) _Pragma("unroll") for (int k = 0; k < 2; ++k) \
;         acc[ai][bj][m][n] = __builtin_amdgcn_mfma_f32_16x16x32_bf16(Bt[n][k], At[m][k], acc[ai][bj][m][n], 0, 0, 0); __builtin_amdgcn_s_setprio(0); } while (0)
; #define PG8_WAIT_V(n) asm volatile("s_waitcnt vmcnt(" #n ")" ::: "memory")
; #define PG8_WAIT_L(n) asm volatile("s_waitcnt lgkmcnt(" #n ")" ::: "memory")
; #define PG8_BAR __builtin_amdgcn_s_barrier()
; #define PG8_SCHED __builtin_amdgcn_sched_barrier(0)
; template <class Epi, class Sched, bool ALIGN_EPI = false, bool SP2 = false>
; __device__ __forceinline__ void gemm_phase(PG8_LAS unsigned char* lds, const Gemm g, const Sched& S, const Epi& E) {
;     ...
;             PG8_WAIT_V(8); PG8_WAIT_L(0); PG8_BAR; PG8_MMA(1, 0, At, B0); PG8_MMA(1, 1, At, B1); PG8_BAR; PG8_SCHED;
;             PG8_LDB(B0, 1, 0); PG8_LDB(B1, 1, 1); PG8_SCHED; PG8_LDA(At, 1, 0); PG8_STAGE(PG8_SA(0, 1), a2 + hstep, voffA);
;             PG8_WAIT_V(8); PG8_WAIT_L(0); PG8_BAR; PG8_MMA(0, 0, At, B0); PG8_MMA(0, 1, At, B1); PG8_BAR; PG8_SCHED;
	s_waitcnt lgkmcnt(0)
	v_mfma_f32_16x16x32_bf16 v[60:63], v[142:145], v[178:181], v[60:63]
	v_mfma_f32_16x16x32_bf16 v[56:59], v[154:157], v[178:181], v[56:59]
	v_mfma_f32_16x16x32_bf16 v[52:55], v[142:145], v[190:193], v[52:55]
	v_mfma_f32_16x16x32_bf16 v[48:51], v[154:157], v[190:193], v[48:51]
	v_mfma_f32_16x16x32_bf16 v[44:47], v[142:145], v[198:201], v[44:47]
	v_mfma_f32_16x16x32_bf16 v[40:43], v[154:157], v[198:201], v[40:43]
	v_mfma_f32_16x16x32_bf16 v[36:39], v[142:145], v[206:209], v[36:39]
	v_mfma_f32_16x16x32_bf16 v[32:35], v[154:157], v[206:209], v[32:35]
	v_mfma_f32_16x16x32_bf16 v[60:63], v[150:153], v[182:185], v[60:63]
	v_mfma_f32_16x16x32_bf16 v[56:59], v[158:161], v[182:185], v[56:59]
	v_mfma_f32_16x16x32_bf16 v[52:55], v[150:153], v[194:197], v[52:55]
	v_mfma_f32_16x16x32_bf16 v[48:51], v[158:161], v[194:197], v[48:51]
	v_mfma_f32_16x16x32_bf16 v[44:47], v[150:153], v[202:205], v[44:47]
	v_mfma_f32_16x16x32_bf16 v[40:43], v[158:161], v[202:205], v[40:43]
	v_mfma_f32_16x16x32_bf16 v[36:39], v[150:153], v[228:231], v[36:39]
	v_mfma_f32_16x16x32_bf16 v[32:35], v[158:161], v[228:231], v[32:35]
	v_mfma_f32_16x16x32_bf16 v[28:31], v[162:165], v[178:181], v[28:31]
	v_mfma_f32_16x16x32_bf16 v[24:27], v[170:173], v[178:181], v[24:27]
	v_mfma_f32_16x16x32_bf16 v[20:23], v[162:165], v[190:193], v[20:23]
	v_mfma_f32_16x16x32_bf16 v[16:19], v[170:173], v[190:193], v[16:19]
	v_mfma_f32_16x16x32_bf16 v[12:15], v[162:165], v[198:201], v[12:15]
	v_mfma_f32_16x16x32_bf16 v[8:11], v[170:173], v[198:201], v[8:11]
	v_mfma_f32_16x16x32_bf16 v[4:7], v[162:165], v[206:209], v[4:7]
	v_mfma_f32_16x16x32_bf16 v[0:3], v[170:173], v[206:209], v[0:3]
	v_mfma_f32_16x16x32_bf16 v[28:31], v[166:169], v[182:185], v[28:31]
	v_mfma_f32_16x16x32_bf16 v[24:27], v[174:177], v[182:185], v[24:27]
	v_mfma_f32_16x16x32_bf16 v[20:23], v[166:169], v[194:197], v[20:23]
	v_mfma_f32_16x16x32_bf16 v[16:19], v[174:177], v[194:197], v[16:19]
	v_mfma_f32_16x16x32_bf16 v[12:15], v[166:169], v[202:205], v[12:15]
	v_mfma_f32_16x16x32_bf16 v[8:11], v[174:177], v[202:205], v[8:11]
	v_mfma_f32_16x16x32_bf16 v[4:7], v[166:169], v[228:231], v[4:7]
	v_mfma_f32_16x16x32_bf16 v[0:3], v[174:177], v[228:231], v[0:3]
	s_barrier
	s_add_i32 s84, 0, 0x18000
	v_add_u32_e32 v140, s84, v146
	s_add_i32 s85, 0, 0x1c000
	ds_read_b128 v[142:145], v140
	ds_read_b128 v[150:153], v140 offset:1024
	ds_read_b128 v[154:157], v140 offset:2048
	ds_read_b128 v[158:161], v140 offset:3072
	v_add_u32_e32 v140, s85, v146
	ds_read_b128 v[162:165], v140
	ds_read_b128 v[166:169], v140 offset:1024
	ds_read_b128 v[170:173], v140 offset:2048
	ds_read_b128 v[174:177], v140 offset:3072
	s_add_u32 s64, s64, 0x40000
	s_addc_u32 s65, s65, 0
	s_mov_b32 m0, s21
	v_lshl_add_u64 v[234:235], s[64:65], 0, v[134:135]
	ds_read_b128 v[178:181], v148 offset:32768
	ds_read_b128 v[182:185], v148 offset:33792
	ds_read_b128 v[190:193], v148 offset:34816
	ds_read_b128 v[194:197], v148 offset:35840
	ds_read_b128 v[198:201], v148 offset:36864
	ds_read_b128 v[202:205], v148 offset:37888
	ds_read_b128 v[206:209], v148 offset:38912
	ds_read_b128 v[228:231], v148 offset:39936
	global_load_lds_dwordx4 v[234:235], off
	v_lshl_add_u64 v[234:235], s[64:65], 0, v[132:133]
	s_mov_b32 m0, s22
	s_nop 0
	global_load_lds_dwordx4 v[234:235], off
	s_waitcnt vmcnt(8)
	s_waitcnt lgkmcnt(0)
	s_barrier
	s_waitcnt lgkmcnt(0)
	v_mfma_f32_16x16x32_bf16 v[124:127], v[142:145], v[178:181], v[124:127]
	v_mfma_f32_16x16x32_bf16 v[120:123], v[154:157], v[178:181], v[120:123]
	v_mfma_f32_16x16x32_bf16 v[116:119], v[142:145], v[190:193], v[116:119]
	v_mfma_f32_16x16x32_bf16 v[112:115], v[154:157], v[190:193], v[112:115]
	v_mfma_f32_16x16x32_bf16 v[108:111], v[142:145], v[198:201], v[108:111]
	v_mfma_f32_16x16x32_bf16 v[104:107], v[154:157], v[198:201], v[104:107]
	v_mfma_f32_16x16x32_bf16 v[100:103], v[142:145], v[206:209], v[100:103]
	v_mfma_f32_16x16x32_bf16 v[96:99], v[154:157], v[206:209], v[96:99]
	v_mfma_f32_16x16x32_bf16 v[124:127], v[150:153], v[182:185], v[124:127]
	v_mfma_f32_16x16x32_bf16 v[120:123], v[158:161], v[182:185], v[120:123]
	v_mfma_f32_16x16x32_bf16 v[116:119], v[150:153], v[194:197], v[116:119]
	v_mfma_f32_16x16x32_bf16 v[112:115], v[158:161], v[194:197], v[112:115]
	v_mfma_f32_16x16x32_bf16 v[108:111], v[150:153], v[202:205], v[108:111]
	v_mfma_f32_16x16x32_bf16 v[104:107], v[158:161], v[202:205], v[104:107]
	v_mfma_f32_16x16x32_bf16 v[100:103], v[150:153], v[228:231], v[100:103]
	v_mfma_f32_16x16x32_bf16 v[96:99], v[158:161], v[228:231], v[96:99]
	v_mfma_f32_16x16x32_bf16 v[92:95], v[162:165], v[178:181], v[92:95]
	v_mfma_f32_16x16x32_bf16 v[88:91], v[170:173], v[178:181], v[88:91]
	v_mfma_f32_16x16x32_bf16 v[84:87], v[162:165], v[190:193], v[84:87]
	v_mfma_f32_16x16x32_bf16 v[80:83], v[170:173], v[190:193], v[80:83]
	v_mfma_f32_16x16x32_bf16 v[76:79], v[162:165], v[198:201], v[76:79]
	v_mfma_f32_16x16x32_bf16 v[72:75], v[170:173], v[198:201], v[72:75]
	v_mfma_f32_16x16x32_bf16 v[68:71], v[162:165], v[206:209], v[68:71]
	v_mfma_f32_16x16x32_bf16 v[64:67], v[170:173], v[206:209], v[64:67]
	v_mfma_f32_16x16x32_bf16 v[92:95], v[166:169], v[182:185], v[92:95]
	v_mfma_f32_16x16x32_bf16 v[88:91], v[174:177], v[182:185], v[88:91]
	v_mfma_f32_16x16x32_bf16 v[84:87], v[166:169], v[194:197], v[84:87]
	v_mfma_f32_16x16x32_bf16 v[80:83], v[174:177], v[194:197], v[80:83]
	v_mfma_f32_16x16x32_bf16 v[76:79], v[166:169], v[202:205], v[76:79]
	v_mfma_f32_16x16x32_bf16 v[72:75], v[174:177], v[202:205], v[72:75]
	v_mfma_f32_16x16x32_bf16 v[68:71], v[166:169], v[228:231], v[68:71]
	v_mfma_f32_16x16x32_bf16 v[64:67], v[174:177], v[228:231], v[64:67]
	s_barrier
; #define PG8_STAGE(bufoff, gbase, voff) do { _Pragma("unroll") for (int _i = 0; _i < 2; ++_i) \
;         __builtin_amdgcn_global_load_lds((const unsigned*)((const char*)(gbase) + (voff)[_i]), (PG8_LAS unsigned*)(lds + (bufoff) + ldsw + _i * 8192), 16, 0, 0); } while (0)
; #define PG8_LDA(dst, b, h) do { _Pragma("unroll") for (int m = 0; m < 4; ++m) _Pragma("unroll") for (int k = 0; k < 2; ++k) dst[m][k] = *(const PG8_LAS bf16x8*)(lds + PG8_SA(b, h) + aoff + m * 2048 + k * 1024); } while (0)
; #define PG8_MMA(ai, bj, At, Bt) do { __builtin_amdgcn_s_setprio(1); _Pragma("unroll") for (int m = 0; m < 4; ++m) _Pragma("unroll") for (int n = 0; n < 2; ++n) _Pragma("unroll") for (int k = 0; k < 2; ++k) \
;         acc[ai][bj][m][n] = __builtin_amdgcn_mfma_f32_16x16x32_bf16(Bt[n][k], At[m][k], acc[ai][bj][m][n], 0, 0, 0); __builtin_amdgcn_s_setprio(0); } while (0)
; #define PG8_WAIT_V(n) asm volatile("s_waitcnt vmcnt(" #n ")" ::: "memory")
; #define PG8_WAIT_L(n) asm volatile("s_waitcnt lgkmcnt(" #n ")" ::: "memory")
; #define PG8_BAR __builtin_amdgcn_s_barrier()
; #define PG8_SCHED __builtin_amdgcn_sched_barrier(0)
; template <class Epi, class Sched, bool ALIGN_EPI = false, bool SP2 = false>
; __device__ __forceinline__ void gemm_phase(PG8_LAS unsigned char* lds, const Gemm g, const Sched& S, const Epi& E) {
;     ...
;         for (int t = 0; t < nt; t += 2) {
;             const bool last = (t == nt - 2);
;     ...
;             PG8_LDA(At, 1, 1); PG8_STAGE(PG8_SB(1, 0), b3, voffB); PG8_STAGE(PG8_SB(1, 1), b3 + hstep, voffB); PG8_STAGE(PG8_SA(1, 0), a3, voffA);
;             PG8_WAIT_V(8); PG8_WAIT_L(0); PG8_BAR; PG8_MMA(1, 0, At, B0); PG8_MMA(1, 1, At, B1); PG8_BAR; PG8_SCHED;
	s_add_i32 s64, s84, s18
	v_lshl_add_u64 v[186:187], v[186:187], 0, s[90:91]
	s_mov_b32 m0, s64
	ds_read_b128 v[178:181], v148 offset:49152
	ds_read_b128 v[182:185], v148 offset:50176
	ds_read_b128 v[190:193], v148 offset:51200
	ds_read_b128 v[194:197], v148 offset:52224
	ds_read_b128 v[198:201], v148 offset:53248
	ds_read_b128 v[202:205], v148 offset:54272
	ds_read_b128 v[206:209], v148 offset:55296
	ds_read_b128 v[228:231], v148 offset:56320
	global_load_lds_dwordx4 v[186:187], off
	s_add_i32 m0, s64, 0x2000
	s_add_u32 s58, s58, 0x40080
	v_lshl_add_u64 v[186:187], v[188:189], 0, s[90:91]
	s_addc_u32 s59, s59, 0
	s_add_i32 s64, s85, s18
	global_load_lds_dwordx4 v[186:187], off
	v_lshl_add_u64 v[186:187], s[58:59], 0, v[128:129]
	s_mov_b32 m0, s64
	s_nop 0
	global_load_lds_dwordx4 v[186:187], off
	v_lshl_add_u64 v[186:187], s[58:59], 0, v[130:131]
	s_add_i32 m0, s64, 0x2000
	s_nop 0
	global_load_lds_dwordx4 v[186:187], off
	v_lshl_add_u64 v[186:187], v[210:211], 0, s[90:91]
	s_mov_b32 m0, s28
	s_nop 0
	global_load_lds_dwordx4 v[186:187], off
	v_lshl_add_u64 v[186:187], v[232:233], 0, s[90:91]
	s_mov_b32 m0, s29
	s_nop 0
	global_load_lds_dwordx4 v[186:187], off
	s_waitcnt vmcnt(8)
	s_waitcnt lgkmcnt(0)
	s_barrier
	s_waitcnt lgkmcnt(0)
	v_mfma_f32_16x16x32_bf16 v[60:63], v[142:145], v[178:181], v[60:63]
	v_mfma_f32_16x16x32_bf16 v[56:59], v[154:157], v[178:181], v[56:59]
	v_mfma_f32_16x16x32_bf16 v[52:55], v[142:145], v[190:193], v[52:55]
	v_mfma_f32_16x16x32_bf16 v[48:51], v[154:157], v[190:193], v[48:51]
	v_mfma_f32_16x16x32_bf16 v[44:47], v[142:145], v[198:201], v[44:47]
	v_mfma_f32_16x16x32_bf16 v[40:43], v[154:157], v[198:201], v[40:43]
	v_mfma_f32_16x16x32_bf16 v[36:39], v[142:145], v[206:209], v[36:39]
	v_mfma_f32_16x16x32_bf16 v[32:35], v[154:157], v[206:209], v[32:35]
	v_mfma_f32_16x16x32_bf16 v[60:63], v[150:153], v[182:185], v[60:63]
	v_mfma_f32_16x16x32_bf16 v[56:59], v[158:161], v[182:185], v[56:59]
	v_mfma_f32_16x16x32_bf16 v[52:55], v[150:153], v[194:197], v[52:55]
	v_mfma_f32_16x16x32_bf16 v[48:51], v[158:161], v[194:197], v[48:51]
	v_mfma_f32_16x16x32_bf16 v[44:47], v[150:153], v[202:205], v[44:47]
	v_mfma_f32_16x16x32_bf16 v[40:43], v[158:161], v[202:205], v[40:43]
	v_mfma_f32_16x16x32_bf16 v[36:39], v[150:153], v[228:231], v[36:39]
	v_mfma_f32_16x16x32_bf16 v[32:35], v[158:161], v[228:231], v[32:35]
	v_mfma_f32_16x16x32_bf16 v[28:31], v[162:165], v[178:181], v[28:31]
	v_mfma_f32_16x16x32_bf16 v[24:27], v[170:173], v[178:181], v[24:27]
	v_mfma_f32_16x16x32_bf16 v[20:23], v[162:165], v[190:193], v[20:23]
	v_mfma_f32_16x16x32_bf16 v[16:19], v[170:173], v[190:193], v[16:19]
	v_mfma_f32_16x16x32_bf16 v[12:15], v[162:165], v[198:201], v[12:15]
	v_mfma_f32_16x16x32_bf16 v[8:11], v[170:173], v[198:201], v[8:11]
	v_mfma_f32_16x16x32_bf16 v[4:7], v[162:165], v[206:209], v[4:7]
	v_mfma_f32_16x16x32_bf16 v[0:3], v[170:173], v[206:209], v[0:3]
	v_mfma_f32_16x16x32_bf16 v[28:31], v[166:169], v[182:185], v[28:31]
	v_mfma_f32_16x16x32_bf16 v[24:27], v[174:177], v[182:185], v[24:27]
	v_mfma_f32_16x16x32_bf16 v[20:23], v[166:169], v[194:197], v[20:23]
	v_mfma_f32_16x16x32_bf16 v[16:19], v[174:177], v[194:197], v[16:19]
	v_mfma_f32_16x16x32_bf16 v[12:15], v[166:169], v[202:205], v[12:15]
	v_mfma_f32_16x16x32_bf16 v[8:11], v[174:177], v[202:205], v[8:11]
	v_mfma_f32_16x16x32_bf16 v[4:7], v[166:169], v[228:231], v[4:7]
	v_mfma_f32_16x16x32_bf16 v[0:3], v[174:177], v[228:231], v[0:3]
	s_add_i32 s94, s94, 2
	s_add_u32 s72, s72, 0x100
	s_addc_u32 s73, s73, 0
	s_add_u32 s92, s92, 0x100
	s_addc_u32 s93, s93, 0

; #define PG8_STAGE(bufoff, gbase, voff) do { _Pragma("unroll") for (int _i = 0; _i < 2; ++_i) \
;         __builtin_amdgcn_global_load_lds((const unsigned*)((const char*)(gbase) + (voff)[_i]), (PG8_LAS unsigned*)(lds + (bufoff) + ldsw + _i * 8192), 16, 0, 0); } while (0)
; #define PG8_LDA(dst, b, h) do { _Pragma("unroll") for (int m = 0; m < 4; ++m) _Pragma("unroll") for (int k = 0; k < 2; ++k) dst[m][k] = *(const PG8_LAS bf16x8*)(lds + PG8_SA(b, h) + aoff + m * 2048 + k * 1024); } while (0)
; #define PG8_LDB(dst, b, h) do { _Pragma("unroll") for (int n = 0; n < 2; ++n) _Pragma("unroll") for (int k = 0; k < 2; ++k) dst[n][k] = *(const PG8_LAS bf16x8*)(lds + PG8_SB(b, h) + boff + n * 2048 + k * 1024); } while (0)
; #define PG8_MMA(ai, bj, At, Bt) do { __builtin_amdgcn_s_setprio(1); _Pragma("unroll") for (int m = 0; m < 4; ++m) _Pragma("unroll") for (int n = 0; n < 2; ++n) _Pragma("unroll") for (int k = 0; k < 2; ++k) \
;         acc[ai][bj][m][n] = __builtin_amdgcn_mfma_f32_16x16x32_bf16(Bt[n][k], At[m][k], acc[ai][bj][m][n], 0, 0, 0); __builtin_amdgcn_s_setprio(0); } while (0)
; #define PG8_WAIT_V(n) asm volatile("s_waitcnt vmcnt(" #n ")" ::: "memory")
; #define PG8_WAIT_L(n) asm volatile("s_waitcnt lgkmcnt(" #n ")" ::: "memory")
; #define PG8_BAR __builtin_amdgcn_s_barrier()
; #define PG8_SCHED __builtin_amdgcn_sched_barrier(0)
; template <class Epi, class Sched, bool ALIGN_EPI = false, bool SP2 = false>
; __device__ __forceinline__ void gemm_phase(PG8_LAS unsigned char* lds, const Gemm g, const Sched& S, const Epi& E) {
;     ...
;             if constexpr (SP2) {
;             PG8_LDB(B0, 0, 0); PG8_LDB(B1, 0, 1); PG8_SCHED; PG8_LDA(At, 0, 0); PG8_STAGE(PG8_SA(1, 1), a1 + hstep, voffA);
;             PG8_WAIT_V(8); PG8_WAIT_L(0); PG8_BAR; PG8_MMA(0, 0, At, B0); PG8_MMA(0, 1, At, B1); PG8_BAR; PG8_SCHED;
;             PG8_LDA(At, 0, 1); PG8_STAGE(PG8_SB(0, 0), b2, voffB); PG8_STAGE(PG8_SB(0, 1), b2 + hstep, voffB); PG8_STAGE(PG8_SA(0, 0), a2, voffA);
;             PG8_WAIT_V(8); PG8_WAIT_L(0); PG8_BAR; PG8_MMA(1, 0, At, B0); PG8_MMA(1, 1, At, B1); PG8_BAR; PG8_SCHED;
.Lsp_0:
	s_add_u32 s8, s66, 0xfffc0080
	s_addc_u32 s37, s67, -1
	s_add_i32 s49, 0, 0x10000
	s_cmp_eq_u32 s36, 12
	s_cselect_b32 s65, s28, s37
	s_cselect_b32 s64, s29, s8
	s_cselect_b32 s59, s30, s35
	s_cselect_b32 s58, s31, s34
	s_add_i32 s8, 0, 0x14000
	v_add_u32_e32 v156, s49, v145
	v_add_u32_e32 v172, s8, v145
	ds_read_b128 v[140:143], v156
	ds_read_b128 v[148:151], v156 offset:1024
	ds_read_b128 v[152:155], v156 offset:2048
	ds_read_b128 v[156:159], v156 offset:3072
	ds_read_b128 v[160:163], v172
	ds_read_b128 v[164:167], v172 offset:1024
	ds_read_b128 v[168:171], v172 offset:2048
	ds_read_b128 v[172:175], v172 offset:3072
	v_lshl_add_u64 v[208:209], s[66:67], 0, v[136:137]
	s_add_i32 m0, s18, 0xc000
	ds_read_b128 v[176:179], v147
	ds_read_b128 v[180:183], v147 offset:1024
	ds_read_b128 v[184:187], v147 offset:2048
	ds_read_b128 v[188:191], v147 offset:3072
	ds_read_b128 v[192:195], v147 offset:4096
	ds_read_b128 v[196:199], v147 offset:5120
	ds_read_b128 v[200:203], v147 offset:6144
	ds_read_b128 v[204:207], v147 offset:7168
	global_load_lds_dwordx4 v[208:209], off
	v_lshl_add_u64 v[208:209], s[66:67], 0, v[138:139]
	s_add_i32 m0, s18, 0xe000
	s_nop 0
	global_load_lds_dwordx4 v[208:209], off
	s_waitcnt vmcnt(8)
	s_waitcnt lgkmcnt(0)
	s_barrier
	s_waitcnt lgkmcnt(0)
	v_mfma_f32_16x16x32_bf16 v[124:127], v[140:143], v[176:179], 0
	v_mfma_f32_16x16x32_bf16 v[116:119], v[152:155], v[176:179], 0
	v_mfma_f32_16x16x32_bf16 v[108:111], v[140:143], v[184:187], 0
	v_mfma_f32_16x16x32_bf16 v[100:103], v[152:155], v[184:187], 0
	v_mfma_f32_16x16x32_bf16 v[92:95], v[140:143], v[192:195], 0
	v_mfma_f32_16x16x32_bf16 v[84:87], v[152:155], v[192:195], 0
	v_mfma_f32_16x16x32_bf16 v[76:79], v[140:143], v[200:203], 0
	v_mfma_f32_16x16x32_bf16 v[68:71], v[152:155], v[200:203], 0
	v_mfma_f32_16x16x32_bf16 v[124:127], v[148:151], v[180:183], v[124:127]
	v_mfma_f32_16x16x32_bf16 v[116:119], v[156:159], v[180:183], v[116:119]
	v_mfma_f32_16x16x32_bf16 v[108:111], v[148:151], v[188:191], v[108:111]
	v_mfma_f32_16x16x32_bf16 v[100:103], v[156:159], v[188:191], v[100:103]
	v_mfma_f32_16x16x32_bf16 v[92:95], v[148:151], v[196:199], v[92:95]
	v_mfma_f32_16x16x32_bf16 v[84:87], v[156:159], v[196:199], v[84:87]
	v_mfma_f32_16x16x32_bf16 v[76:79], v[148:151], v[204:207], v[76:79]
	v_mfma_f32_16x16x32_bf16 v[68:71], v[156:159], v[204:207], v[68:71]
	v_mfma_f32_16x16x32_bf16 v[120:123], v[160:163], v[176:179], 0
	v_mfma_f32_16x16x32_bf16 v[112:115], v[168:171], v[176:179], 0
	v_mfma_f32_16x16x32_bf16 v[104:107], v[160:163], v[184:187], 0
	v_mfma_f32_16x16x32_bf16 v[96:99], v[168:171], v[184:187], 0
	v_mfma_f32_16x16x32_bf16 v[88:91], v[160:163], v[192:195], 0
	v_mfma_f32_16x16x32_bf16 v[80:83], v[168:171], v[192:195], 0
	v_mfma_f32_16x16x32_bf16 v[72:75], v[160:163], v[200:203], 0
	v_mfma_f32_16x16x32_bf16 v[64:67], v[168:171], v[200:203], 0
	v_mfma_f32_16x16x32_bf16 v[120:123], v[164:167], v[180:183], v[120:123]
	v_mfma_f32_16x16x32_bf16 v[112:115], v[172:175], v[180:183], v[112:115]
	v_mfma_f32_16x16x32_bf16 v[104:107], v[164:167], v[188:191], v[104:107]
	v_mfma_f32_16x16x32_bf16 v[96:99], v[172:175], v[188:191], v[96:99]
	v_mfma_f32_16x16x32_bf16 v[88:91], v[164:167], v[196:199], v[88:91]
	v_mfma_f32_16x16x32_bf16 v[80:83], v[172:175], v[196:199], v[80:83]
	v_mfma_f32_16x16x32_bf16 v[72:75], v[164:167], v[204:207], v[72:75]
	v_mfma_f32_16x16x32_bf16 v[64:67], v[172:175], v[204:207], v[64:67]
	s_barrier
	s_add_i32 s37, s49, s17
	v_lshl_add_u64 v[208:209], s[58:59], 0, v[128:129]
	s_mov_b32 m0, s37
	ds_read_b128 v[176:179], v147 offset:16384
	ds_read_b128 v[180:183], v147 offset:17408
	ds_read_b128 v[184:187], v147 offset:18432
	ds_read_b128 v[188:191], v147 offset:19456
	ds_read_b128 v[192:195], v147 offset:20480
	ds_read_b128 v[196:199], v147 offset:21504
	ds_read_b128 v[200:203], v147 offset:22528
	ds_read_b128 v[204:207], v147 offset:23552
	global_load_lds_dwordx4 v[208:209], off
	s_add_i32 m0, s37, 0x2000
	s_add_u32 s72, s58, 0x40000
	v_lshl_add_u64 v[210:211], s[58:59], 0, v[130:131]
	s_addc_u32 s73, s59, 0
	s_add_i32 s8, s8, s17
	global_load_lds_dwordx4 v[210:211], off
	v_lshl_add_u64 v[214:215], s[72:73], 0, v[128:129]
	s_mov_b32 m0, s8
	v_lshl_add_u64 v[222:223], s[64:65], 0, v[132:133]
	global_load_lds_dwordx4 v[214:215], off
	v_lshl_add_u64 v[214:215], s[72:73], 0, v[130:131]
	s_add_i32 m0, s8, 0x2000
	s_nop 0
	global_load_lds_dwordx4 v[214:215], off
	v_lshl_add_u64 v[214:215], s[64:65], 0, v[134:135]
	s_mov_b32 m0, s18
	s_nop 0
	global_load_lds_dwordx4 v[214:215], off
	s_mov_b32 m0, s19
	s_nop 0
	global_load_lds_dwordx4 v[222:223], off
	s_waitcnt vmcnt(8)
	s_waitcnt lgkmcnt(0)
	s_barrier
; #define PG8_STAGE(bufoff, gbase, voff) do { _Pragma("unroll") for (int _i = 0; _i < 2; ++_i) \
;         __builtin_amdgcn_global_load_lds((const unsigned*)((const char*)(gbase) + (voff)[_i]), (PG8_LAS unsigned*)(lds + (bufoff) + ldsw + _i * 8192), 16, 0, 0); } while (0)
; #define PG8_LDA(dst, b, h) do { _Pragma("unroll") for (int m = 0; m < 4; ++m) _Pragma("unroll") for (int k = 0; k < 2; ++k) dst[m][k] = *(const PG8_LAS bf16x8*)(lds + PG8_SA(b, h) + aoff + m * 2048 + k * 1024); } while (0)
; #define PG8_LDB(dst, b, h) do { _Pragma("unroll") for (int n = 0; n < 2; ++n) _Pragma("unroll") for (int k = 0; k < 2; ++k) dst[n][k] = *(const PG8_LAS bf16x8*)(lds + PG8_SB(b, h) + boff + n * 2048 + k * 1024); } while (0)
; #define PG8_MMA(ai, bj, At, Bt) do { __builtin_amdgcn_s_setprio(1); _Pragma("unroll") for (int m = 0; m < 4; ++m) _Pragma("unroll") for (int n = 0; n < 2; ++n) _Pragma("unroll") for (int k = 0; k < 2; ++k) \
;         acc[ai][bj][m][n] = __builtin_amdgcn_mfma_f32_16x16x32_bf16(Bt[n][k], At[m][k], acc[ai][bj][m][n], 0, 0, 0); __builtin_amdgcn_s_setprio(0); } while (0)
; #define PG8_WAIT_V(n) asm volatile("s_waitcnt vmcnt(" #n ")" ::: "memory")
; #define PG8_WAIT_L(n) asm volatile("s_waitcnt lgkmcnt(" #n ")" ::: "memory")
; #define PG8_BAR __builtin_amdgcn_s_barrier()
; #define PG8_SCHED __builtin_amdgcn_sched_barrier(0)
; template <class Epi, class Sched, bool ALIGN_EPI = false, bool SP2 = false>
; __device__ __forceinline__ void gemm_phase(PG8_LAS unsigned char* lds, const Gemm g, const Sched& S, const Epi& E) {
;     ...
;             PG8_WAIT_V(8); PG8_WAIT_L(0); PG8_BAR; PG8_MMA(1, 0, At, B0); PG8_MMA(1, 1, At, B1); PG8_BAR; PG8_SCHED;
;             PG8_LDB(B0, 1, 0); PG8_LDB(B1, 1, 1); PG8_SCHED; PG8_LDA(At, 1, 0); PG8_STAGE(PG8_SA(0, 1), a2 + hstep, voffA);
;             PG8_WAIT_V(8); PG8_WAIT_L(0); PG8_BAR; PG8_MMA(0, 0, At, B0); PG8_MMA(0, 1, At, B1); PG8_BAR; PG8_SCHED;
	s_waitcnt lgkmcnt(0)
	v_mfma_f32_16x16x32_bf16 v[60:63], v[140:143], v[176:179], 0
	v_mfma_f32_16x16x32_bf16 v[52:55], v[152:155], v[176:179], 0
	v_mfma_f32_16x16x32_bf16 v[44:47], v[140:143], v[184:187], 0
	v_mfma_f32_16x16x32_bf16 v[36:39], v[152:155], v[184:187], 0
	v_mfma_f32_16x16x32_bf16 v[28:31], v[140:143], v[192:195], 0
	v_mfma_f32_16x16x32_bf16 v[20:23], v[152:155], v[192:195], 0
	v_mfma_f32_16x16x32_bf16 v[12:15], v[140:143], v[200:203], 0
	v_mfma_f32_16x16x32_bf16 v[4:7], v[152:155], v[200:203], 0
	v_mfma_f32_16x16x32_bf16 v[60:63], v[148:151], v[180:183], v[60:63]
	v_mfma_f32_16x16x32_bf16 v[52:55], v[156:159], v[180:183], v[52:55]
	v_mfma_f32_16x16x32_bf16 v[44:47], v[148:151], v[188:191], v[44:47]
	v_mfma_f32_16x16x32_bf16 v[36:39], v[156:159], v[188:191], v[36:39]
	v_mfma_f32_16x16x32_bf16 v[28:31], v[148:151], v[196:199], v[28:31]
	v_mfma_f32_16x16x32_bf16 v[20:23], v[156:159], v[196:199], v[20:23]
	v_mfma_f32_16x16x32_bf16 v[12:15], v[148:151], v[204:207], v[12:15]
	v_mfma_f32_16x16x32_bf16 v[4:7], v[156:159], v[204:207], v[4:7]
	v_mfma_f32_16x16x32_bf16 v[56:59], v[160:163], v[176:179], 0
	v_mfma_f32_16x16x32_bf16 v[48:51], v[168:171], v[176:179], 0
	v_mfma_f32_16x16x32_bf16 v[40:43], v[160:163], v[184:187], 0
	v_mfma_f32_16x16x32_bf16 v[32:35], v[168:171], v[184:187], 0
	v_mfma_f32_16x16x32_bf16 v[24:27], v[160:163], v[192:195], 0
	v_mfma_f32_16x16x32_bf16 v[16:19], v[168:171], v[192:195], 0
	v_mfma_f32_16x16x32_bf16 v[8:11], v[160:163], v[200:203], 0
	v_mfma_f32_16x16x32_bf16 v[0:3], v[168:171], v[200:203], 0
	v_mfma_f32_16x16x32_bf16 v[56:59], v[164:167], v[180:183], v[56:59]
	v_mfma_f32_16x16x32_bf16 v[48:51], v[172:175], v[180:183], v[48:51]
	v_mfma_f32_16x16x32_bf16 v[40:43], v[164:167], v[188:191], v[40:43]
	v_mfma_f32_16x16x32_bf16 v[32:35], v[172:175], v[188:191], v[32:35]
	v_mfma_f32_16x16x32_bf16 v[24:27], v[164:167], v[196:199], v[24:27]
	v_mfma_f32_16x16x32_bf16 v[16:19], v[172:175], v[196:199], v[16:19]
	v_mfma_f32_16x16x32_bf16 v[8:11], v[164:167], v[204:207], v[8:11]
	v_mfma_f32_16x16x32_bf16 v[0:3], v[172:175], v[204:207], v[0:3]
	s_barrier
	s_add_i32 s8, 0, 0x18000
	s_add_i32 s37, 0, 0x1c000
	v_add_u32_e32 v156, s8, v145
	v_add_u32_e32 v172, s37, v145
	ds_read_b128 v[140:143], v156
	ds_read_b128 v[148:151], v156 offset:1024
	ds_read_b128 v[152:155], v156 offset:2048
	ds_read_b128 v[156:159], v156 offset:3072
	ds_read_b128 v[160:163], v172
	ds_read_b128 v[164:167], v172 offset:1024
	ds_read_b128 v[168:171], v172 offset:2048
	ds_read_b128 v[172:175], v172 offset:3072
	s_add_u32 s64, s64, 0x40000
	s_addc_u32 s65, s65, 0
	s_mov_b32 m0, s20
	v_lshl_add_u64 v[228:229], s[64:65], 0, v[134:135]
	ds_read_b128 v[176:179], v147 offset:32768
	ds_read_b128 v[180:183], v147 offset:33792
	ds_read_b128 v[184:187], v147 offset:34816
	ds_read_b128 v[188:191], v147 offset:35840
	ds_read_b128 v[192:195], v147 offset:36864
	ds_read_b128 v[196:199], v147 offset:37888
	ds_read_b128 v[200:203], v147 offset:38912
	ds_read_b128 v[204:207], v147 offset:39936
	global_load_lds_dwordx4 v[228:229], off
	v_lshl_add_u64 v[228:229], s[64:65], 0, v[132:133]
	s_mov_b32 m0, s21
	s_nop 0
	global_load_lds_dwordx4 v[228:229], off
	s_waitcnt vmcnt(8)
	s_waitcnt lgkmcnt(0)
	s_barrier
	s_waitcnt lgkmcnt(0)
	v_mfma_f32_16x16x32_bf16 v[124:127], v[140:143], v[176:179], v[124:127]
	v_mfma_f32_16x16x32_bf16 v[116:119], v[152:155], v[176:179], v[116:119]
	v_mfma_f32_16x16x32_bf16 v[108:111], v[140:143], v[184:187], v[108:111]
	v_mfma_f32_16x16x32_bf16 v[100:103], v[152:155], v[184:187], v[100:103]
	v_mfma_f32_16x16x32_bf16 v[92:95], v[140:143], v[192:195], v[92:95]
	v_mfma_f32_16x16x32_bf16 v[84:87], v[152:155], v[192:195], v[84:87]
	v_mfma_f32_16x16x32_bf16 v[76:79], v[140:143], v[200:203], v[76:79]
	v_mfma_f32_16x16x32_bf16 v[68:71], v[152:155], v[200:203], v[68:71]
	v_mfma_f32_16x16x32_bf16 v[124:127], v[148:151], v[180:183], v[124:127]
	v_mfma_f32_16x16x32_bf16 v[116:119], v[156:159], v[180:183], v[116:119]
	v_mfma_f32_16x16x32_bf16 v[108:111], v[148:151], v[188:191], v[108:111]
	v_mfma_f32_16x16x32_bf16 v[100:103], v[156:159], v[188:191], v[100:103]
	v_mfma_f32_16x16x32_bf16 v[92:95], v[148:151], v[196:199], v[92:95]
	v_mfma_f32_16x16x32_bf16 v[84:87], v[156:159], v[196:199], v[84:87]
	v_mfma_f32_16x16x32_bf16 v[76:79], v[148:151], v[204:207], v[76:79]
	v_mfma_f32_16x16x32_bf16 v[68:71], v[156:159], v[204:207], v[68:71]
	v_mfma_f32_16x16x32_bf16 v[120:123], v[160:163], v[176:179], v[120:123]
	v_mfma_f32_16x16x32_bf16 v[112:115], v[168:171], v[176:179], v[112:115]
	v_mfma_f32_16x16x32_bf16 v[104:107], v[160:163], v[184:187], v[104:107]
	v_mfma_f32_16x16x32_bf16 v[96:99], v[168:171], v[184:187], v[96:99]
	v_mfma_f32_16x16x32_bf16 v[88:91], v[160:163], v[192:195], v[88:91]
	v_mfma_f32_16x16x32_bf16 v[80:83], v[168:171], v[192:195], v[80:83]
	v_mfma_f32_16x16x32_bf16 v[72:75], v[160:163], v[200:203], v[72:75]
	v_mfma_f32_16x16x32_bf16 v[64:67], v[168:171], v[200:203], v[64:67]
	v_mfma_f32_16x16x32_bf16 v[120:123], v[164:167], v[180:183], v[120:123]
	v_mfma_f32_16x16x32_bf16 v[112:115], v[172:175], v[180:183], v[112:115]
	v_mfma_f32_16x16x32_bf16 v[104:107], v[164:167], v[188:191], v[104:107]
	v_mfma_f32_16x16x32_bf16 v[96:99], v[172:175], v[188:191], v[96:99]
	v_mfma_f32_16x16x32_bf16 v[88:91], v[164:167], v[196:199], v[88:91]
	v_mfma_f32_16x16x32_bf16 v[80:83], v[172:175], v[196:199], v[80:83]
	v_mfma_f32_16x16x32_bf16 v[72:75], v[164:167], v[204:207], v[72:75]
	v_mfma_f32_16x16x32_bf16 v[64:67], v[172:175], v[204:207], v[64:67]
	s_barrier
; #define PG8_STAGE(bufoff, gbase, voff) do { _Pragma("unroll") for (int _i = 0; _i < 2; ++_i) \
;         __builtin_amdgcn_global_load_lds((const unsigned*)((const char*)(gbase) + (voff)[_i]), (PG8_LAS unsigned*)(lds + (bufoff) + ldsw + _i * 8192), 16, 0, 0); } while (0)
; #define PG8_LDA(dst, b, h) do { _Pragma("unroll") for (int m = 0; m < 4; ++m) _Pragma("unroll") for (int k = 0; k < 2; ++k) dst[m][k] = *(const PG8_LAS bf16x8*)(lds + PG8_SA(b, h) + aoff + m * 2048 + k * 1024); } while (0)
; #define PG8_LDB(dst, b, h) do { _Pragma("unroll") for (int n = 0; n < 2; ++n) _Pragma("unroll") for (int k = 0; k < 2; ++k) dst[n][k] = *(const PG8_LAS bf16x8*)(lds + PG8_SB(b, h) + boff + n * 2048 + k * 1024); } while (0)
; template <class Epi, class Sched, bool ALIGN_EPI = false, bool SP2 = false>
; __device__ __forceinline__ void gemm_phase(PG8_LAS unsigned char* lds, const Gemm g, const Sched& S, const Epi& E) {
;     ...
;         for (int t = 0; t < nt; t += 2) {
;             const bool last = (t == nt - 2);
;             const char* a1 = cA + (size_t)(t + 1) * kstep;
;             const char* a2 = last ? nA : cA + (size_t)(t + 2) * kstep; const char* b2 = last ? nB : cB + (size_t)(t + 2) * kstep;
;             const char* a3 = a2 + kstep; const char* b3 = b2 + kstep;
;             if (last && has_next) S.a_ready(nxt);
;             if constexpr (SP2) {
;             PG8_LDB(B0, 0, 0); PG8_LDB(B1, 0, 1); PG8_SCHED; PG8_LDA(At, 0, 0); PG8_STAGE(PG8_SA(1, 1), a1 + hstep, voffA);
;             PG8_WAIT_V(8); PG8_WAIT_L(0); PG8_BAR; PG8_MMA(0, 0, At, B0); PG8_MMA(0, 1, At, B1); PG8_BAR; PG8_SCHED;
;             PG8_LDA(At, 0, 1); PG8_STAGE(PG8_SB(0, 0), b2, voffB); PG8_STAGE(PG8_SB(0, 1), b2 + hstep, voffB); PG8_STAGE(PG8_SA(0, 0), a2, voffA);
;             PG8_WAIT_V(8); PG8_WAIT_L(0); PG8_BAR; PG8_MMA(1, 0, At, B0); PG8_MMA(1, 1, At, B1); PG8_BAR; PG8_SCHED;
;             PG8_LDB(B0, 1, 0); PG8_LDB(B1, 1, 1); PG8_SCHED; PG8_LDA(At, 1, 0); PG8_STAGE(PG8_SA(0, 1), a2 + hstep, voffA);
;             PG8_WAIT_V(8); PG8_WAIT_L(0); PG8_BAR; PG8_MMA(0, 0, At, B0); PG8_MMA(0, 1, At, B1); PG8_BAR; PG8_SCHED;
;             PG8_LDA(At, 1, 1); PG8_STAGE(PG8_SB(1, 0), b3, voffB); PG8_STAGE(PG8_SB(1, 1), b3 + hstep, voffB); PG8_STAGE(PG8_SA(1, 0), a3, voffA);
;             PG8_WAIT_V(8); PG8_WAIT_L(0); PG8_BAR; PG8_MMA(1, 0, At, B0); PG8_MMA(1, 1, At, B1); PG8_BAR; PG8_SCHED;
	s_add_i32 s8, s8, s17
	v_lshl_add_u64 v[208:209], v[208:209], 0, s[90:91]
	s_mov_b32 m0, s8
	ds_read_b128 v[176:179], v147 offset:49152
	ds_read_b128 v[180:183], v147 offset:50176
	ds_read_b128 v[184:187], v147 offset:51200
	ds_read_b128 v[188:191], v147 offset:52224
	ds_read_b128 v[192:195], v147 offset:53248
	ds_read_b128 v[196:199], v147 offset:54272
	ds_read_b128 v[200:203], v147 offset:55296
	ds_read_b128 v[204:207], v147 offset:56320
	global_load_lds_dwordx4 v[208:209], off
	s_add_i32 m0, s8, 0x2000
	s_add_u32 s58, s58, 0x40080
	v_lshl_add_u64 v[208:209], v[210:211], 0, s[90:91]
	s_addc_u32 s59, s59, 0
	s_add_i32 s8, s37, s17
	global_load_lds_dwordx4 v[208:209], off
	v_lshl_add_u64 v[208:209], s[58:59], 0, v[128:129]
	s_mov_b32 m0, s8
	s_nop 0
	global_load_lds_dwordx4 v[208:209], off
	v_lshl_add_u64 v[208:209], s[58:59], 0, v[130:131]
	s_add_i32 m0, s8, 0x2000
	s_nop 0
	global_load_lds_dwordx4 v[208:209], off
	v_lshl_add_u64 v[208:209], v[214:215], 0, s[90:91]
	s_mov_b32 m0, s22
	s_nop 0
	global_load_lds_dwordx4 v[208:209], off
	v_lshl_add_u64 v[208:209], v[222:223], 0, s[90:91]
	s_mov_b32 m0, s23
	s_nop 0
	global_load_lds_dwordx4 v[208:209], off
	s_waitcnt vmcnt(8)
	s_waitcnt lgkmcnt(0)
	s_barrier
	s_waitcnt lgkmcnt(0)
	v_mfma_f32_16x16x32_bf16 v[60:63], v[140:143], v[176:179], v[60:63]
	v_mfma_f32_16x16x32_bf16 v[52:55], v[152:155], v[176:179], v[52:55]
	v_mfma_f32_16x16x32_bf16 v[44:47], v[140:143], v[184:187], v[44:47]
	v_mfma_f32_16x16x32_bf16 v[36:39], v[152:155], v[184:187], v[36:39]
	v_mfma_f32_16x16x32_bf16 v[28:31], v[140:143], v[192:195], v[28:31]
	v_mfma_f32_16x16x32_bf16 v[20:23], v[152:155], v[192:195], v[20:23]
	v_mfma_f32_16x16x32_bf16 v[12:15], v[140:143], v[200:203], v[12:15]
	v_mfma_f32_16x16x32_bf16 v[4:7], v[152:155], v[200:203], v[4:7]
	v_mfma_f32_16x16x32_bf16 v[60:63], v[148:151], v[180:183], v[60:63]
	v_mfma_f32_16x16x32_bf16 v[52:55], v[156:159], v[180:183], v[52:55]
	v_mfma_f32_16x16x32_bf16 v[44:47], v[148:151], v[188:191], v[44:47]
	v_mfma_f32_16x16x32_bf16 v[36:39], v[156:159], v[188:191], v[36:39]
	v_mfma_f32_16x16x32_bf16 v[28:31], v[148:151], v[196:199], v[28:31]
	v_mfma_f32_16x16x32_bf16 v[20:23], v[156:159], v[196:199], v[20:23]
	v_mfma_f32_16x16x32_bf16 v[12:15], v[148:151], v[204:207], v[12:15]
	v_mfma_f32_16x16x32_bf16 v[4:7], v[156:159], v[204:207], v[4:7]
	v_mfma_f32_16x16x32_bf16 v[56:59], v[160:163], v[176:179], v[56:59]
	v_mfma_f32_16x16x32_bf16 v[48:51], v[168:171], v[176:179], v[48:51]
	v_mfma_f32_16x16x32_bf16 v[40:43], v[160:163], v[184:187], v[40:43]
	v_mfma_f32_16x16x32_bf16 v[32:35], v[168:171], v[184:187], v[32:35]
	v_mfma_f32_16x16x32_bf16 v[24:27], v[160:163], v[192:195], v[24:27]
	v_mfma_f32_16x16x32_bf16 v[16:19], v[168:171], v[192:195], v[16:19]
	v_mfma_f32_16x16x32_bf16 v[8:11], v[160:163], v[200:203], v[8:11]
	v_mfma_f32_16x16x32_bf16 v[0:3], v[168:171], v[200:203], v[0:3]
	v_mfma_f32_16x16x32_bf16 v[56:59], v[164:167], v[180:183], v[56:59]
	v_mfma_f32_16x16x32_bf16 v[48:51], v[172:175], v[180:183], v[48:51]
	v_mfma_f32_16x16x32_bf16 v[40:43], v[164:167], v[188:191], v[40:43]
	v_mfma_f32_16x16x32_bf16 v[32:35], v[172:175], v[188:191], v[32:35]
	v_mfma_f32_16x16x32_bf16 v[24:27], v[164:167], v[196:199], v[24:27]
	v_mfma_f32_16x16x32_bf16 v[16:19], v[172:175], v[196:199], v[16:19]
	v_mfma_f32_16x16x32_bf16 v[8:11], v[164:167], v[204:207], v[8:11]
	v_mfma_f32_16x16x32_bf16 v[0:3], v[172:175], v[204:207], v[0:3]
	s_barrier
	s_add_i32 s36, s36, 2
	s_add_u32 s66, s66, 0x100
	s_addc_u32 s67, s67, 0
	s_add_u32 s34, s34, 0x100
	s_addc_u32 s35, s35, 0
	s_cmp_gt_u32 s36, 11
	s_cbranch_scc1 .Lklast_0
.LBB0_813:
	s_add_u32 s8, s66, 0xfffc0080
	s_addc_u32 s37, s67, -1
	s_add_i32 s49, 0, 0x10000
	s_cmp_eq_u32 s36, 12
	s_cselect_b32 s65, s28, s37
	s_cselect_b32 s64, s29, s8
	s_cselect_b32 s59, s30, s35
	s_cselect_b32 s58, s31, s34
	s_add_i32 s8, 0, 0x14000
	v_add_u32_e32 v156, s49, v145
	v_add_u32_e32 v172, s8, v145
	ds_read_b128 v[140:143], v156
	ds_read_b128 v[148:151], v156 offset:1024
	ds_read_b128 v[152:155], v156 offset:2048
	ds_read_b128 v[156:159], v156 offset:3072
	ds_read_b128 v[160:163], v172
	ds_read_b128 v[164:167], v172 offset:1024
	ds_read_b128 v[168:171], v172 offset:2048
	ds_read_b128 v[172:175], v172 offset:3072
	v_lshl_add_u64 v[208:209], s[66:67], 0, v[136:137]
	s_add_i32 m0, s18, 0xc000
	ds_read_b128 v[176:179], v147
	ds_read_b128 v[180:183], v147 offset:1024
	ds_read_b128 v[184:187], v147 offset:2048
	ds_read_b128 v[188:191], v147 offset:3072
	ds_read_b128 v[192:195], v147 offset:4096
	ds_read_b128 v[196:199], v147 offset:5120
	ds_read_b128 v[200:203], v147 offset:6144
	ds_read_b128 v[204:207], v147 offset:7168
	global_load_lds_dwordx4 v[208:209], off
	v_lshl_add_u64 v[208:209], s[66:67], 0, v[138:139]
	s_add_i32 m0, s18, 0xe000
	s_nop 0
	global_load_lds_dwordx4 v[208:209], off
	s_waitcnt vmcnt(8)
	s_waitcnt lgkmcnt(0)
	s_barrier
; #define PG8_STAGE(bufoff, gbase, voff) do { _Pragma("unroll") for (int _i = 0; _i < 2; ++_i) \
;         __builtin_amdgcn_global_load_lds((const unsigned*)((const char*)(gbase) + (voff)[_i]), (PG8_LAS unsigned*)(lds + (bufoff) + ldsw + _i * 8192), 16, 0, 0); } while (0)
; #define PG8_LDA(dst, b, h) do { _Pragma("unroll") for (int m = 0; m < 4; ++m) _Pragma("unroll") for (int k = 0; k < 2; ++k) dst[m][k] = *(const PG8_LAS bf16x8*)(lds + PG8_SA(b, h) + aoff + m * 2048 + k * 1024); } while (0)
; #define PG8_LDB(dst, b, h) do { _Pragma("unroll") for (int n = 0; n < 2; ++n) _Pragma("unroll") for (int k = 0; k < 2; ++k) dst[n][k] = *(const PG8_LAS bf16x8*)(lds + PG8_SB(b, h) + boff + n * 2048 + k * 1024); } while (0)
; #define PG8_MMA(ai, bj, At, Bt) do { __builtin_amdgcn_s_setprio(1); _Pragma("unroll") for (int m = 0; m < 4; ++m) _Pragma("unroll") for (int n = 0; n < 2; ++n) _Pragma("unroll") for (int k = 0; k < 2; ++k) \
;         acc[ai][bj][m][n] = __builtin_amdgcn_mfma_f32_16x16x32_bf16(Bt[n][k], At[m][k], acc[ai][bj][m][n], 0, 0, 0); __builtin_amdgcn_s_setprio(0); } while (0)
; #define PG8_BAR __builtin_amdgcn_s_barrier()
; template <class Epi, class Sched, bool ALIGN_EPI = false, bool SP2 = false>
; __device__ __forceinline__ void gemm_phase(PG8_LAS unsigned char* lds, const Gemm g, const Sched& S, const Epi& E) {
;     ...
;             if constexpr (SP2) {
;             PG8_LDB(B0, 0, 0); PG8_LDB(B1, 0, 1); PG8_SCHED; PG8_LDA(At, 0, 0); PG8_STAGE(PG8_SA(1, 1), a1 + hstep, voffA);
;             PG8_WAIT_V(8); PG8_WAIT_L(0); PG8_BAR; PG8_MMA(0, 0, At, B0); PG8_MMA(0, 1, At, B1); PG8_BAR; PG8_SCHED;
;             PG8_LDA(At, 0, 1); PG8_STAGE(PG8_SB(0, 0), b2, voffB); PG8_STAGE(PG8_SB(0, 1), b2 + hstep, voffB); PG8_STAGE(PG8_SA(0, 0), a2, voffA);
;             PG8_WAIT_V(8); PG8_WAIT_L(0); PG8_BAR; PG8_MMA(1, 0, At, B0); PG8_MMA(1, 1, At, B1); PG8_BAR; PG8_SCHED;
;             PG8_LDB(B0, 1, 0); PG8_LDB(B1, 1, 1); PG8_SCHED; PG8_LDA(At, 1, 0); PG8_STAGE(PG8_SA(0, 1), a2 + hstep, voffA);
;             PG8_WAIT_V(8); PG8_WAIT_L(0); PG8_BAR; PG8_MMA(0, 0, At, B0); PG8_MMA(0, 1, At, B1); PG8_BAR; PG8_SCHED;
;             PG8_LDA(At, 1, 1); PG8_STAGE(PG8_SB(1, 0), b3, voffB); PG8_STAGE(PG8_SB(1, 1), b3 + hstep, voffB); PG8_STAGE(PG8_SA(1, 0), a3, voffA);
;             PG8_WAIT_V(8); PG8_WAIT_L(0); PG8_BAR; PG8_MMA(1, 0, At, B0); PG8_MMA(1, 1, At, B1); PG8_BAR; PG8_SCHED;
	s_waitcnt lgkmcnt(0)
	v_mfma_f32_16x16x32_bf16 v[124:127], v[140:143], v[176:179], v[124:127]
	v_mfma_f32_16x16x32_bf16 v[116:119], v[152:155], v[176:179], v[116:119]
	v_mfma_f32_16x16x32_bf16 v[108:111], v[140:143], v[184:187], v[108:111]
	v_mfma_f32_16x16x32_bf16 v[100:103], v[152:155], v[184:187], v[100:103]
	v_mfma_f32_16x16x32_bf16 v[92:95], v[140:143], v[192:195], v[92:95]
	v_mfma_f32_16x16x32_bf16 v[84:87], v[152:155], v[192:195], v[84:87]
	v_mfma_f32_16x16x32_bf16 v[76:79], v[140:143], v[200:203], v[76:79]
	v_mfma_f32_16x16x32_bf16 v[68:71], v[152:155], v[200:203], v[68:71]
	v_mfma_f32_16x16x32_bf16 v[124:127], v[148:151], v[180:183], v[124:127]
	v_mfma_f32_16x16x32_bf16 v[116:119], v[156:159], v[180:183], v[116:119]
	v_mfma_f32_16x16x32_bf16 v[108:111], v[148:151], v[188:191], v[108:111]
	v_mfma_f32_16x16x32_bf16 v[100:103], v[156:159], v[188:191], v[100:103]
	v_mfma_f32_16x16x32_bf16 v[92:95], v[148:151], v[196:199], v[92:95]
	v_mfma_f32_16x16x32_bf16 v[84:87], v[156:159], v[196:199], v[84:87]
	v_mfma_f32_16x16x32_bf16 v[76:79], v[148:151], v[204:207], v[76:79]
	v_mfma_f32_16x16x32_bf16 v[68:71], v[156:159], v[204:207], v[68:71]
	v_mfma_f32_16x16x32_bf16 v[120:123], v[160:163], v[176:179], v[120:123]
	v_mfma_f32_16x16x32_bf16 v[112:115], v[168:171], v[176:179], v[112:115]
	v_mfma_f32_16x16x32_bf16 v[104:107], v[160:163], v[184:187], v[104:107]
	v_mfma_f32_16x16x32_bf16 v[96:99], v[168:171], v[184:187], v[96:99]
	v_mfma_f32_16x16x32_bf16 v[88:91], v[160:163], v[192:195], v[88:91]
	v_mfma_f32_16x16x32_bf16 v[80:83], v[168:171], v[192:195], v[80:83]
	v_mfma_f32_16x16x32_bf16 v[72:75], v[160:163], v[200:203], v[72:75]
	v_mfma_f32_16x16x32_bf16 v[64:67], v[168:171], v[200:203], v[64:67]
	v_mfma_f32_16x16x32_bf16 v[120:123], v[164:167], v[180:183], v[120:123]
	v_mfma_f32_16x16x32_bf16 v[112:115], v[172:175], v[180:183], v[112:115]
	v_mfma_f32_16x16x32_bf16 v[104:107], v[164:167], v[188:191], v[104:107]
	v_mfma_f32_16x16x32_bf16 v[96:99], v[172:175], v[188:191], v[96:99]
	v_mfma_f32_16x16x32_bf16 v[88:91], v[164:167], v[196:199], v[88:91]
	v_mfma_f32_16x16x32_bf16 v[80:83], v[172:175], v[196:199], v[80:83]
	v_mfma_f32_16x16x32_bf16 v[72:75], v[164:167], v[204:207], v[72:75]
	v_mfma_f32_16x16x32_bf16 v[64:67], v[172:175], v[204:207], v[64:67]
	s_barrier
	s_add_i32 s37, s49, s17
	v_lshl_add_u64 v[208:209], s[58:59], 0, v[128:129]
	s_mov_b32 m0, s37
	ds_read_b128 v[176:179], v147 offset:16384
	ds_read_b128 v[180:183], v147 offset:17408
	ds_read_b128 v[184:187], v147 offset:18432
	ds_read_b128 v[188:191], v147 offset:19456
	ds_read_b128 v[192:195], v147 offset:20480
	ds_read_b128 v[196:199], v147 offset:21504
	ds_read_b128 v[200:203], v147 offset:22528
	ds_read_b128 v[204:207], v147 offset:23552
	global_load_lds_dwordx4 v[208:209], off
	s_add_i32 m0, s37, 0x2000
	s_add_u32 s72, s58, 0x40000
	v_lshl_add_u64 v[210:211], s[58:59], 0, v[130:131]
	s_addc_u32 s73, s59, 0
	s_add_i32 s8, s8, s17
	global_load_lds_dwordx4 v[210:211], off
	v_lshl_add_u64 v[214:215], s[72:73], 0, v[128:129]
	s_mov_b32 m0, s8
	v_lshl_add_u64 v[222:223], s[64:65], 0, v[132:133]
	global_load_lds_dwordx4 v[214:215], off
	v_lshl_add_u64 v[214:215], s[72:73], 0, v[130:131]
	s_add_i32 m0, s8, 0x2000
	s_nop 0
	global_load_lds_dwordx4 v[214:215], off
	v_lshl_add_u64 v[214:215], s[64:65], 0, v[134:135]
	s_mov_b32 m0, s18
	s_nop 0
	global_load_lds_dwordx4 v[214:215], off
	s_mov_b32 m0, s19
	s_nop 0
	global_load_lds_dwordx4 v[222:223], off
	s_waitcnt vmcnt(8)
	s_waitcnt lgkmcnt(0)
	s_barrier
	s_waitcnt lgkmcnt(0)
	v_mfma_f32_16x16x32_bf16 v[60:63], v[140:143], v[176:179], v[60:63]
	v_mfma_f32_16x16x32_bf16 v[52:55], v[152:155], v[176:179], v[52:55]
	v_mfma_f32_16x16x32_bf16 v[44:47], v[140:143], v[184:187], v[44:47]
	v_mfma_f32_16x16x32_bf16 v[36:39], v[152:155], v[184:187], v[36:39]
	v_mfma_f32_16x16x32_bf16 v[28:31], v[140:143], v[192:195], v[28:31]
	v_mfma_f32_16x16x32_bf16 v[20:23], v[152:155], v[192:195], v[20:23]
	v_mfma_f32_16x16x32_bf16 v[12:15], v[140:143], v[200:203], v[12:15]
	v_mfma_f32_16x16x32_bf16 v[4:7], v[152:155], v[200:203], v[4:7]
	v_mfma_f32_16x16x32_bf16 v[60:63], v[148:151], v[180:183], v[60:63]
	v_mfma_f32_16x16x32_bf16 v[52:55], v[156:159], v[180:183], v[52:55]
	v_mfma_f32_16x16x32_bf16 v[44:47], v[148:151], v[188:191], v[44:47]
	v_mfma_f32_16x16x32_bf16 v[36:39], v[156:159], v[188:191], v[36:39]
	v_mfma_f32_16x16x32_bf16 v[28:31], v[148:151], v[196:199], v[28:31]
	v_mfma_f32_16x16x32_bf16 v[20:23], v[156:159], v[196:199], v[20:23]
	v_mfma_f32_16x16x32_bf16 v[12:15], v[148:151], v[204:207], v[12:15]
	v_mfma_f32_16x16x32_bf16 v[4:7], v[156:159], v[204:207], v[4:7]
	v_mfma_f32_16x16x32_bf16 v[56:59], v[160:163], v[176:179], v[56:59]
	v_mfma_f32_16x16x32_bf16 v[48:51], v[168:171], v[176:179], v[48:51]
	v_mfma_f32_16x16x32_bf16 v[40:43], v[160:163], v[184:187], v[40:43]
	v_mfma_f32_16x16x32_bf16 v[32:35], v[168:171], v[184:187], v[32:35]
	v_mfma_f32_16x16x32_bf16 v[24:27], v[160:163], v[192:195], v[24:27]
	v_mfma_f32_16x16x32_bf16 v[16:19], v[168:171], v[192:195], v[16:19]
	v_mfma_f32_16x16x32_bf16 v[8:11], v[160:163], v[200:203], v[8:11]
	v_mfma_f32_16x16x32_bf16 v[0:3], v[168:171], v[200:203], v[0:3]
	v_mfma_f32_16x16x32_bf16 v[56:59], v[164:167], v[180:183], v[56:59]
	v_mfma_f32_16x16x32_bf16 v[48:51], v[172:175], v[180:183], v[48:51]
	v_mfma_f32_16x16x32_bf16 v[40:43], v[164:167], v[188:191], v[40:43]
	v_mfma_f32_16x16x32_bf16 v[32:35], v[172:175], v[188:191], v[32:35]
	v_mfma_f32_16x16x32_bf16 v[24:27], v[164:167], v[196:199], v[24:27]
	v_mfma_f32_16x16x32_bf16 v[16:19], v[172:175], v[196:199], v[16:19]
	v_mfma_f32_16x16x32_bf16 v[8:11], v[164:167], v[204:207], v[8:11]
	v_mfma_f32_16x16x32_bf16 v[0:3], v[172:175], v[204:207], v[0:3]
	s_barrier
; #define PG8_STAGE(bufoff, gbase, voff) do { _Pragma("unroll") for (int _i = 0; _i < 2; ++_i) \
;         __builtin_amdgcn_global_load_lds((const unsigned*)((const char*)(gbase) + (voff)[_i]), (PG8_LAS unsigned*)(lds + (bufoff) + ldsw + _i * 8192), 16, 0, 0); } while (0)
; #define PG8_LDA(dst, b, h) do { _Pragma("unroll") for (int m = 0; m < 4; ++m) _Pragma("unroll") for (int k = 0; k < 2; ++k) dst[m][k] = *(const PG8_LAS bf16x8*)(lds + PG8_SA(b, h) + aoff + m * 2048 + k * 1024); } while (0)
; #define PG8_LDB(dst, b, h) do { _Pragma("unroll") for (int n = 0; n < 2; ++n) _Pragma("unroll") for (int k = 0; k < 2; ++k) dst[n][k] = *(const PG8_LAS bf16x8*)(lds + PG8_SB(b, h) + boff + n * 2048 + k * 1024); } while (0)
; template <class Epi, class Sched, bool ALIGN_EPI = false, bool SP2 = false>
; __device__ __forceinline__ void gemm_phase(PG8_LAS unsigned char* lds, const Gemm g, const Sched& S, const Epi& E) {
;     ...
;         for (int t = 0; t < nt; t += 2) {
;             const bool last = (t == nt - 2);
;             const char* a1 = cA + (size_t)(t + 1) * kstep;
;             const char* a2 = last ? nA : cA + (size_t)(t + 2) * kstep; const char* b2 = last ? nB : cB + (size_t)(t + 2) * kstep;
;             const char* a3 = a2 + kstep; const char* b3 = b2 + kstep;
;             if (last && has_next) S.a_ready(nxt);
;             if constexpr (SP2) {
;             PG8_LDB(B0, 0, 0); PG8_LDB(B1, 0, 1); PG8_SCHED; PG8_LDA(At, 0, 0); PG8_STAGE(PG8_SA(1, 1), a1 + hstep, voffA);
;             PG8_WAIT_V(8); PG8_WAIT_L(0); PG8_BAR; PG8_MMA(0, 0, At, B0); PG8_MMA(0, 1, At, B1); PG8_BAR; PG8_SCHED;
;             PG8_LDA(At, 0, 1); PG8_STAGE(PG8_SB(0, 0), b2, voffB); PG8_STAGE(PG8_SB(0, 1), b2 + hstep, voffB); PG8_STAGE(PG8_SA(0, 0), a2, voffA);
;             PG8_WAIT_V(8); PG8_WAIT_L(0); PG8_BAR; PG8_MMA(1, 0, At, B0); PG8_MMA(1, 1, At, B1); PG8_BAR; PG8_SCHED;
;             PG8_LDB(B0, 1, 0); PG8_LDB(B1, 1, 1); PG8_SCHED; PG8_LDA(At, 1, 0); PG8_STAGE(PG8_SA(0, 1), a2 + hstep, voffA);
;             PG8_WAIT_V(8); PG8_WAIT_L(0); PG8_BAR; PG8_MMA(0, 0, At, B0); PG8_MMA(0, 1, At, B1); PG8_BAR; PG8_SCHED;
;             PG8_LDA(At, 1, 1); PG8_STAGE(PG8_SB(1, 0), b3, voffB); PG8_STAGE(PG8_SB(1, 1), b3 + hstep, voffB); PG8_STAGE(PG8_SA(1, 0), a3, voffA);
;             PG8_WAIT_V(8); PG8_WAIT_L(0); PG8_BAR; PG8_MMA(1, 0, At, B0); PG8_MMA(1, 1, At, B1); PG8_BAR; PG8_SCHED;
	s_add_i32 s8, 0, 0x18000
	s_add_i32 s37, 0, 0x1c000
	v_add_u32_e32 v156, s8, v145
	v_add_u32_e32 v172, s37, v145
	ds_read_b128 v[140:143], v156
	ds_read_b128 v[148:151], v156 offset:1024
	ds_read_b128 v[152:155], v156 offset:2048
	ds_read_b128 v[156:159], v156 offset:3072
	ds_read_b128 v[160:163], v172
	ds_read_b128 v[164:167], v172 offset:1024
	ds_read_b128 v[168:171], v172 offset:2048
	ds_read_b128 v[172:175], v172 offset:3072
	s_add_u32 s64, s64, 0x40000
	s_addc_u32 s65, s65, 0
	s_mov_b32 m0, s20
	v_lshl_add_u64 v[228:229], s[64:65], 0, v[134:135]
	ds_read_b128 v[176:179], v147 offset:32768
	ds_read_b128 v[180:183], v147 offset:33792
	ds_read_b128 v[184:187], v147 offset:34816
	ds_read_b128 v[188:191], v147 offset:35840
	ds_read_b128 v[192:195], v147 offset:36864
	ds_read_b128 v[196:199], v147 offset:37888
	ds_read_b128 v[200:203], v147 offset:38912
	ds_read_b128 v[204:207], v147 offset:39936
	global_load_lds_dwordx4 v[228:229], off
	v_lshl_add_u64 v[228:229], s[64:65], 0, v[132:133]
	s_mov_b32 m0, s21
	s_nop 0
	global_load_lds_dwordx4 v[228:229], off
	s_waitcnt vmcnt(8)
	s_waitcnt lgkmcnt(0)
	s_barrier
	s_waitcnt lgkmcnt(0)
	v_mfma_f32_16x16x32_bf16 v[124:127], v[140:143], v[176:179], v[124:127]
	v_mfma_f32_16x16x32_bf16 v[116:119], v[152:155], v[176:179], v[116:119]
	v_mfma_f32_16x16x32_bf16 v[108:111], v[140:143], v[184:187], v[108:111]
	v_mfma_f32_16x16x32_bf16 v[100:103], v[152:155], v[184:187], v[100:103]
	v_mfma_f32_16x16x32_bf16 v[92:95], v[140:143], v[192:195], v[92:95]
	v_mfma_f32_16x16x32_bf16 v[84:87], v[152:155], v[192:195], v[84:87]
	v_mfma_f32_16x16x32_bf16 v[76:79], v[140:143], v[200:203], v[76:79]
	v_mfma_f32_16x16x32_bf16 v[68:71], v[152:155], v[200:203], v[68:71]
	v_mfma_f32_16x16x32_bf16 v[124:127], v[148:151], v[180:183], v[124:127]
	v_mfma_f32_16x16x32_bf16 v[116:119], v[156:159], v[180:183], v[116:119]
	v_mfma_f32_16x16x32_bf16 v[108:111], v[148:151], v[188:191], v[108:111]
	v_mfma_f32_16x16x32_bf16 v[100:103], v[156:159], v[188:191], v[100:103]
	v_mfma_f32_16x16x32_bf16 v[92:95], v[148:151], v[196:199], v[92:95]
	v_mfma_f32_16x16x32_bf16 v[84:87], v[156:159], v[196:199], v[84:87]
	v_mfma_f32_16x16x32_bf16 v[76:79], v[148:151], v[204:207], v[76:79]
	v_mfma_f32_16x16x32_bf16 v[68:71], v[156:159], v[204:207], v[68:71]
	v_mfma_f32_16x16x32_bf16 v[120:123], v[160:163], v[176:179], v[120:123]
	v_mfma_f32_16x16x32_bf16 v[112:115], v[168:171], v[176:179], v[112:115]
	v_mfma_f32_16x16x32_bf16 v[104:107], v[160:163], v[184:187], v[104:107]
	v_mfma_f32_16x16x32_bf16 v[96:99], v[168:171], v[184:187], v[96:99]
	v_mfma_f32_16x16x32_bf16 v[88:91], v[160:163], v[192:195], v[88:91]
	v_mfma_f32_16x16x32_bf16 v[80:83], v[168:171], v[192:195], v[80:83]
	v_mfma_f32_16x16x32_bf16 v[72:75], v[160:163], v[200:203], v[72:75]
	v_mfma_f32_16x16x32_bf16 v[64:67], v[168:171], v[200:203], v[64:67]
	v_mfma_f32_16x16x32_bf16 v[120:123], v[164:167], v[180:183], v[120:123]
	v_mfma_f32_16x16x32_bf16 v[112:115], v[172:175], v[180:183], v[112:115]
	v_mfma_f32_16x16x32_bf16 v[104:107], v[164:167], v[188:191], v[104:107]
	v_mfma_f32_16x16x32_bf16 v[96:99], v[172:175], v[188:191], v[96:99]
	v_mfma_f32_16x16x32_bf16 v[88:91], v[164:167], v[196:199], v[88:91]
	v_mfma_f32_16x16x32_bf16 v[80:83], v[172:175], v[196:199], v[80:83]
	v_mfma_f32_16x16x32_bf16 v[72:75], v[164:167], v[204:207], v[72:75]
	v_mfma_f32_16x16x32_bf16 v[64:67], v[172:175], v[204:207], v[64:67]
	s_barrier
	s_add_i32 s8, s8, s17
	v_lshl_add_u64 v[208:209], v[208:209], 0, s[90:91]
	s_mov_b32 m0, s8
	ds_read_b128 v[176:179], v147 offset:49152
	ds_read_b128 v[180:183], v147 offset:50176
	ds_read_b128 v[184:187], v147 offset:51200
	ds_read_b128 v[188:191], v147 offset:52224
	ds_read_b128 v[192:195], v147 offset:53248
	ds_read_b128 v[196:199], v147 offset:54272
	ds_read_b128 v[200:203], v147 offset:55296
	ds_read_b128 v[204:207], v147 offset:56320
	global_load_lds_dwordx4 v[208:209], off
	s_add_i32 m0, s8, 0x2000
	s_add_u32 s58, s58, 0x40080
	v_lshl_add_u64 v[208:209], v[210:211], 0, s[90:91]
	s_addc_u32 s59, s59, 0
	s_add_i32 s8, s37, s17
	global_load_lds_dwordx4 v[208:209], off
	v_lshl_add_u64 v[208:209], s[58:59], 0, v[128:129]
	s_mov_b32 m0, s8
	s_nop 0
	global_load_lds_dwordx4 v[208:209], off
	v_lshl_add_u64 v[208:209], s[58:59], 0, v[130:131]
	s_add_i32 m0, s8, 0x2000
	s_nop 0
	global_load_lds_dwordx4 v[208:209], off
	v_lshl_add_u64 v[208:209], v[214:215], 0, s[90:91]
	s_mov_b32 m0, s22
	s_nop 0
	global_load_lds_dwordx4 v[208:209], off
	v_lshl_add_u64 v[208:209], v[222:223], 0, s[90:91]
	s_mov_b32 m0, s23
	s_nop 0
	global_load_lds_dwordx4 v[208:209], off
	s_waitcnt vmcnt(8)
	s_waitcnt lgkmcnt(0)
	s_barrier
	s_waitcnt lgkmcnt(0)
	v_mfma_f32_16x16x32_bf16 v[60:63], v[140:143], v[176:179], v[60:63]
	v_mfma_f32_16x16x32_bf16 v[52:55], v[152:155], v[176:179], v[52:55]
	v_mfma_f32_16x16x32_bf16 v[44:47], v[140:143], v[184:187], v[44:47]
	v_mfma_f32_16x16x32_bf16 v[36:39], v[152:155], v[184:187], v[36:39]
	v_mfma_f32_16x16x32_bf16 v[28:31], v[140:143], v[192:195], v[28:31]
	v_mfma_f32_16x16x32_bf16 v[20:23], v[152:155], v[192:195], v[20:23]
	v_mfma_f32_16x16x32_bf16 v[12:15], v[140:143], v[200:203], v[12:15]
	v_mfma_f32_16x16x32_bf16 v[4:7], v[152:155], v[200:203], v[4:7]
	v_mfma_f32_16x16x32_bf16 v[60:63], v[148:151], v[180:183], v[60:63]
	v_mfma_f32_16x16x32_bf16 v[52:55], v[156:159], v[180:183], v[52:55]
	v_mfma_f32_16x16x32_bf16 v[44:47], v[148:151], v[188:191], v[44:47]
	v_mfma_f32_16x16x32_bf16 v[36:39], v[156:159], v[188:191], v[36:39]
	v_mfma_f32_16x16x32_bf16 v[28:31], v[148:151], v[196:199], v[28:31]
	v_mfma_f32_16x16x32_bf16 v[20:23], v[156:159], v[196:199], v[20:23]
	v_mfma_f32_16x16x32_bf16 v[12:15], v[148:151], v[204:207], v[12:15]
	v_mfma_f32_16x16x32_bf16 v[4:7], v[156:159], v[204:207], v[4:7]
	v_mfma_f32_16x16x32_bf16 v[56:59], v[160:163], v[176:179], v[56:59]
	v_mfma_f32_16x16x32_bf16 v[48:51], v[168:171], v[176:179], v[48:51]
	v_mfma_f32_16x16x32_bf16 v[40:43], v[160:163], v[184:187], v[40:43]
	v_mfma_f32_16x16x32_bf16 v[32:35], v[168:171], v[184:187], v[32:35]
	v_mfma_f32_16x16x32_bf16 v[24:27], v[160:163], v[192:195], v[24:27]
	v_mfma_f32_16x16x32_bf16 v[16:19], v[168:171], v[192:195], v[16:19]
	v_mfma_f32_16x16x32_bf16 v[8:11], v[160:163], v[200:203], v[8:11]
	v_mfma_f32_16x16x32_bf16 v[0:3], v[168:171], v[200:203], v[0:3]
	v_mfma_f32_16x16x32_bf16 v[56:59], v[164:167], v[180:183], v[56:59]
	v_mfma_f32_16x16x32_bf16 v[48:51], v[172:175], v[180:183], v[48:51]
	v_mfma_f32_16x16x32_bf16 v[40:43], v[164:167], v[188:191], v[40:43]
	v_mfma_f32_16x16x32_bf16 v[32:35], v[172:175], v[188:191], v[32:35]
	v_mfma_f32_16x16x32_bf16 v[24:27], v[164:167], v[196:199], v[24:27]
	v_mfma_f32_16x16x32_bf16 v[16:19], v[172:175], v[196:199], v[16:19]
	v_mfma_f32_16x16x32_bf16 v[8:11], v[164:167], v[204:207], v[8:11]
	v_mfma_f32_16x16x32_bf16 v[0:3], v[172:175], v[204:207], v[0:3]
	s_barrier
	s_add_i32 s36, s36, 2
	s_add_u32 s66, s66, 0x100
	s_addc_u32 s67, s67, 0
	s_add_u32 s34, s34, 0x100
	s_addc_u32 s35, s35, 0
	s_cmp_gt_u32 s36, 11
	s_cbranch_scc0 .LBB0_813
; #define PG8_STAGE(bufoff, gbase, voff) do { _Pragma("unroll") for (int _i = 0; _i < 2; ++_i) \
;         __builtin_amdgcn_global_load_lds((const unsigned*)((const char*)(gbase) + (voff)[_i]), (PG8_LAS unsigned*)(lds + (bufoff) + ldsw + _i * 8192), 16, 0, 0); } while (0)
; #define PG8_LDA(dst, b, h) do { _Pragma("unroll") for (int m = 0; m < 4; ++m) _Pragma("unroll") for (int k = 0; k < 2; ++k) dst[m][k] = *(const PG8_LAS bf16x8*)(lds + PG8_SA(b, h) + aoff + m * 2048 + k * 1024); } while (0)
; #define PG8_LDB(dst, b, h) do { _Pragma("unroll") for (int n = 0; n < 2; ++n) _Pragma("unroll") for (int k = 0; k < 2; ++k) dst[n][k] = *(const PG8_LAS bf16x8*)(lds + PG8_SB(b, h) + boff + n * 2048 + k * 1024); } while (0)
; #define PG8_MMA(ai, bj, At, Bt) do { __builtin_amdgcn_s_setprio(1); _Pragma("unroll") for (int m = 0; m < 4; ++m) _Pragma("unroll") for (int n = 0; n < 2; ++n) _Pragma("unroll") for (int k = 0; k < 2; ++k) \
;         acc[ai][bj][m][n] = __builtin_amdgcn_mfma_f32_16x16x32_bf16(Bt[n][k], At[m][k], acc[ai][bj][m][n], 0, 0, 0); __builtin_amdgcn_s_setprio(0); } while (0)
; #define PG8_BAR __builtin_amdgcn_s_barrier()
; template <class Epi, class Sched, bool ALIGN_EPI = false, bool SP2 = false>
; __device__ __forceinline__ void gemm_phase(PG8_LAS unsigned char* lds, const Gemm g, const Sched& S, const Epi& E) {
;     ...
;             if constexpr (SP2) {
;             PG8_LDB(B0, 0, 0); PG8_LDB(B1, 0, 1); PG8_SCHED; PG8_LDA(At, 0, 0); PG8_STAGE(PG8_SA(1, 1), a1 + hstep, voffA);
;             PG8_WAIT_V(8); PG8_WAIT_L(0); PG8_BAR; PG8_MMA(0, 0, At, B0); PG8_MMA(0, 1, At, B1); PG8_BAR; PG8_SCHED;
;             PG8_LDA(At, 0, 1); PG8_STAGE(PG8_SB(0, 0), b2, voffB); PG8_STAGE(PG8_SB(0, 1), b2 + hstep, voffB); PG8_STAGE(PG8_SA(0, 0), a2, voffA);
;             PG8_WAIT_V(8); PG8_WAIT_L(0); PG8_BAR; PG8_MMA(1, 0, At, B0); PG8_MMA(1, 1, At, B1); PG8_BAR; PG8_SCHED;
;             PG8_LDB(B0, 1, 0); PG8_LDB(B1, 1, 1); PG8_SCHED; PG8_LDA(At, 1, 0); PG8_STAGE(PG8_SA(0, 1), a2 + hstep, voffA);
;             PG8_WAIT_V(8); PG8_WAIT_L(0); PG8_BAR; PG8_MMA(0, 0, At, B0); PG8_MMA(0, 1, At, B1); PG8_BAR; PG8_SCHED;
;             PG8_LDA(At, 1, 1); PG8_STAGE(PG8_SB(1, 0), b3, voffB); PG8_STAGE(PG8_SB(1, 1), b3 + hstep, voffB); PG8_STAGE(PG8_SA(1, 0), a3, voffA);
;             PG8_WAIT_V(8); PG8_WAIT_L(0); PG8_BAR; PG8_MMA(1, 0, At, B0); PG8_MMA(1, 1, At, B1); PG8_BAR; PG8_SCHED;
.Lklast_0:
	s_add_u32 s8, s66, 0xfffc0080
	s_addc_u32 s37, s67, -1
	s_add_i32 s49, 0, 0x10000
	s_cmp_eq_u32 s36, 12
	s_cselect_b32 s65, s28, s37
	s_cselect_b32 s64, s29, s8
	s_cselect_b32 s59, s30, s35
	s_cselect_b32 s58, s31, s34
	s_add_i32 s8, 0, 0x14000
	v_add_u32_e32 v156, s49, v145
	v_add_u32_e32 v172, s8, v145
	ds_read_b128 v[140:143], v156
	ds_read_b128 v[148:151], v156 offset:1024
	ds_read_b128 v[152:155], v156 offset:2048
	ds_read_b128 v[156:159], v156 offset:3072
	ds_read_b128 v[160:163], v172
	ds_read_b128 v[164:167], v172 offset:1024
	ds_read_b128 v[168:171], v172 offset:2048
	ds_read_b128 v[172:175], v172 offset:3072
	v_lshl_add_u64 v[208:209], s[66:67], 0, v[136:137]
	s_add_i32 m0, s18, 0xc000
	ds_read_b128 v[176:179], v147
	ds_read_b128 v[180:183], v147 offset:1024
	ds_read_b128 v[184:187], v147 offset:2048
	ds_read_b128 v[188:191], v147 offset:3072
	ds_read_b128 v[192:195], v147 offset:4096
	ds_read_b128 v[196:199], v147 offset:5120
	ds_read_b128 v[200:203], v147 offset:6144
	ds_read_b128 v[204:207], v147 offset:7168
	global_load_lds_dwordx4 v[208:209], off
	v_lshl_add_u64 v[208:209], s[66:67], 0, v[138:139]
	s_add_i32 m0, s18, 0xe000
	s_nop 0
	global_load_lds_dwordx4 v[208:209], off
	s_waitcnt vmcnt(8)
	s_waitcnt lgkmcnt(0)
	s_barrier
	s_waitcnt lgkmcnt(0)
	v_mfma_f32_16x16x32_bf16 v[124:127], v[140:143], v[176:179], v[124:127]
	v_mfma_f32_16x16x32_bf16 v[116:119], v[152:155], v[176:179], v[116:119]
	v_mfma_f32_16x16x32_bf16 v[108:111], v[140:143], v[184:187], v[108:111]
	v_mfma_f32_16x16x32_bf16 v[100:103], v[152:155], v[184:187], v[100:103]
	v_mfma_f32_16x16x32_bf16 v[92:95], v[140:143], v[192:195], v[92:95]
	v_mfma_f32_16x16x32_bf16 v[84:87], v[152:155], v[192:195], v[84:87]
	v_mfma_f32_16x16x32_bf16 v[76:79], v[140:143], v[200:203], v[76:79]
	v_mfma_f32_16x16x32_bf16 v[68:71], v[152:155], v[200:203], v[68:71]
	v_mfma_f32_16x16x32_bf16 v[124:127], v[148:151], v[180:183], v[124:127]
	v_mfma_f32_16x16x32_bf16 v[116:119], v[156:159], v[180:183], v[116:119]
	v_mfma_f32_16x16x32_bf16 v[108:111], v[148:151], v[188:191], v[108:111]
	v_mfma_f32_16x16x32_bf16 v[100:103], v[156:159], v[188:191], v[100:103]
	v_mfma_f32_16x16x32_bf16 v[92:95], v[148:151], v[196:199], v[92:95]
	v_mfma_f32_16x16x32_bf16 v[84:87], v[156:159], v[196:199], v[84:87]
	v_mfma_f32_16x16x32_bf16 v[76:79], v[148:151], v[204:207], v[76:79]
	v_mfma_f32_16x16x32_bf16 v[68:71], v[156:159], v[204:207], v[68:71]
	v_mfma_f32_16x16x32_bf16 v[120:123], v[160:163], v[176:179], v[120:123]
	v_mfma_f32_16x16x32_bf16 v[112:115], v[168:171], v[176:179], v[112:115]
	v_mfma_f32_16x16x32_bf16 v[104:107], v[160:163], v[184:187], v[104:107]
	v_mfma_f32_16x16x32_bf16 v[96:99], v[168:171], v[184:187], v[96:99]
	v_mfma_f32_16x16x32_bf16 v[88:91], v[160:163], v[192:195], v[88:91]
	v_mfma_f32_16x16x32_bf16 v[80:83], v[168:171], v[192:195], v[80:83]
	v_mfma_f32_16x16x32_bf16 v[72:75], v[160:163], v[200:203], v[72:75]
	v_mfma_f32_16x16x32_bf16 v[64:67], v[168:171], v[200:203], v[64:67]
	v_mfma_f32_16x16x32_bf16 v[120:123], v[164:167], v[180:183], v[120:123]
	v_mfma_f32_16x16x32_bf16 v[112:115], v[172:175], v[180:183], v[112:115]
	v_mfma_f32_16x16x32_bf16 v[104:107], v[164:167], v[188:191], v[104:107]
	v_mfma_f32_16x16x32_bf16 v[96:99], v[172:175], v[188:191], v[96:99]
	v_mfma_f32_16x16x32_bf16 v[88:91], v[164:167], v[196:199], v[88:91]
	v_mfma_f32_16x16x32_bf16 v[80:83], v[172:175], v[196:199], v[80:83]
	v_mfma_f32_16x16x32_bf16 v[72:75], v[164:167], v[204:207], v[72:75]
	v_mfma_f32_16x16x32_bf16 v[64:67], v[172:175], v[204:207], v[64:67]
	s_barrier
	s_add_i32 s37, s49, s17
	v_lshl_add_u64 v[208:209], s[58:59], 0, v[128:129]
	s_mov_b32 m0, s37
	ds_read_b128 v[176:179], v147 offset:16384
	ds_read_b128 v[180:183], v147 offset:17408
	ds_read_b128 v[184:187], v147 offset:18432
	ds_read_b128 v[188:191], v147 offset:19456
	ds_read_b128 v[192:195], v147 offset:20480
	ds_read_b128 v[196:199], v147 offset:21504
	ds_read_b128 v[200:203], v147 offset:22528
	ds_read_b128 v[204:207], v147 offset:23552
	global_load_lds_dwordx4 v[208:209], off
	s_add_i32 m0, s37, 0x2000
	s_add_u32 s72, s58, 0x40000
	v_lshl_add_u64 v[210:211], s[58:59], 0, v[130:131]
	s_addc_u32 s73, s59, 0
	s_add_i32 s8, s8, s17
	global_load_lds_dwordx4 v[210:211], off
	v_lshl_add_u64 v[214:215], s[72:73], 0, v[128:129]
	s_mov_b32 m0, s8
	v_lshl_add_u64 v[222:223], s[64:65], 0, v[132:133]
	global_load_lds_dwordx4 v[214:215], off
	v_lshl_add_u64 v[214:215], s[72:73], 0, v[130:131]
	s_add_i32 m0, s8, 0x2000
	s_nop 0
	global_load_lds_dwordx4 v[214:215], off
	v_lshl_add_u64 v[214:215], s[64:65], 0, v[134:135]
	s_mov_b32 m0, s18
	s_nop 0
	global_load_lds_dwordx4 v[214:215], off
	s_mov_b32 m0, s19
	s_nop 0
	global_load_lds_dwordx4 v[222:223], off
	s_waitcnt vmcnt(8)
	s_waitcnt lgkmcnt(0)
	s_barrier
; #define PG8_STAGE(bufoff, gbase, voff) do { _Pragma("unroll") for (int _i = 0; _i < 2; ++_i) \
;         __builtin_amdgcn_global_load_lds((const unsigned*)((const char*)(gbase) + (voff)[_i]), (PG8_LAS unsigned*)(lds + (bufoff) + ldsw + _i * 8192), 16, 0, 0); } while (0)
; #define PG8_LDA(dst, b, h) do { _Pragma("unroll") for (int m = 0; m < 4; ++m) _Pragma("unroll") for (int k = 0; k < 2; ++k) dst[m][k] = *(const PG8_LAS bf16x8*)(lds + PG8_SA(b, h) + aoff + m * 2048 + k * 1024); } while (0)
; #define PG8_LDB(dst, b, h) do { _Pragma("unroll") for (int n = 0; n < 2; ++n) _Pragma("unroll") for (int k = 0; k < 2; ++k) dst[n][k] = *(const PG8_LAS bf16x8*)(lds + PG8_SB(b, h) + boff + n * 2048 + k * 1024); } while (0)
; #define PG8_MMA(ai, bj, At, Bt) do { __builtin_amdgcn_s_setprio(1); _Pragma("unroll") for (int m = 0; m < 4; ++m) _Pragma("unroll") for (int n = 0; n < 2; ++n) _Pragma("unroll") for (int k = 0; k < 2; ++k) \
;         acc[ai][bj][m][n] = __builtin_amdgcn_mfma_f32_16x16x32_bf16(Bt[n][k], At[m][k], acc[ai][bj][m][n], 0, 0, 0); __builtin_amdgcn_s_setprio(0); } while (0)
; #define PG8_BAR __builtin_amdgcn_s_barrier()
; template <class Epi, class Sched, bool ALIGN_EPI = false, bool SP2 = false>
; __device__ __forceinline__ void gemm_phase(PG8_LAS unsigned char* lds, const Gemm g, const Sched& S, const Epi& E) {
;     ...
;             if constexpr (SP2) {
;             PG8_LDB(B0, 0, 0); PG8_LDB(B1, 0, 1); PG8_SCHED; PG8_LDA(At, 0, 0); PG8_STAGE(PG8_SA(1, 1), a1 + hstep, voffA);
;             PG8_WAIT_V(8); PG8_WAIT_L(0); PG8_BAR; PG8_MMA(0, 0, At, B0); PG8_MMA(0, 1, At, B1); PG8_BAR; PG8_SCHED;
;             PG8_LDA(At, 0, 1); PG8_STAGE(PG8_SB(0, 0), b2, voffB); PG8_STAGE(PG8_SB(0, 1), b2 + hstep, voffB); PG8_STAGE(PG8_SA(0, 0), a2, voffA);
;             PG8_WAIT_V(8); PG8_WAIT_L(0); PG8_BAR; PG8_MMA(1, 0, At, B0); PG8_MMA(1, 1, At, B1); PG8_BAR; PG8_SCHED;
;             PG8_LDB(B0, 1, 0); PG8_LDB(B1, 1, 1); PG8_SCHED; PG8_LDA(At, 1, 0); PG8_STAGE(PG8_SA(0, 1), a2 + hstep, voffA);
;             PG8_WAIT_V(8); PG8_WAIT_L(0); PG8_BAR; PG8_MMA(0, 0, At, B0); PG8_MMA(0, 1, At, B1); PG8_BAR; PG8_SCHED;
;             PG8_LDA(At, 1, 1); PG8_STAGE(PG8_SB(1, 0), b3, voffB); PG8_STAGE(PG8_SB(1, 1), b3 + hstep, voffB); PG8_STAGE(PG8_SA(1, 0), a3, voffA);
;             PG8_WAIT_V(8); PG8_WAIT_L(0); PG8_BAR; PG8_MMA(1, 0, At, B0); PG8_MMA(1, 1, At, B1); PG8_BAR; PG8_SCHED;
	s_waitcnt lgkmcnt(0)
	v_mfma_f32_16x16x32_bf16 v[60:63], v[140:143], v[176:179], v[60:63]
	v_mfma_f32_16x16x32_bf16 v[52:55], v[152:155], v[176:179], v[52:55]
	v_mfma_f32_16x16x32_bf16 v[44:47], v[140:143], v[184:187], v[44:47]
	v_mfma_f32_16x16x32_bf16 v[36:39], v[152:155], v[184:187], v[36:39]
	v_mfma_f32_16x16x32_bf16 v[28:31], v[140:143], v[192:195], v[28:31]
	v_mfma_f32_16x16x32_bf16 v[20:23], v[152:155], v[192:195], v[20:23]
	v_mfma_f32_16x16x32_bf16 v[12:15], v[140:143], v[200:203], v[12:15]
	v_mfma_f32_16x16x32_bf16 v[4:7], v[152:155], v[200:203], v[4:7]
	v_mfma_f32_16x16x32_bf16 v[60:63], v[148:151], v[180:183], v[60:63]
	v_mfma_f32_16x16x32_bf16 v[52:55], v[156:159], v[180:183], v[52:55]
	v_mfma_f32_16x16x32_bf16 v[44:47], v[148:151], v[188:191], v[44:47]
	v_mfma_f32_16x16x32_bf16 v[36:39], v[156:159], v[188:191], v[36:39]
	v_mfma_f32_16x16x32_bf16 v[28:31], v[148:151], v[196:199], v[28:31]
	v_mfma_f32_16x16x32_bf16 v[20:23], v[156:159], v[196:199], v[20:23]
	v_mfma_f32_16x16x32_bf16 v[12:15], v[148:151], v[204:207], v[12:15]
	v_mfma_f32_16x16x32_bf16 v[4:7], v[156:159], v[204:207], v[4:7]
	v_mfma_f32_16x16x32_bf16 v[56:59], v[160:163], v[176:179], v[56:59]
	v_mfma_f32_16x16x32_bf16 v[48:51], v[168:171], v[176:179], v[48:51]
	v_mfma_f32_16x16x32_bf16 v[40:43], v[160:163], v[184:187], v[40:43]
	v_mfma_f32_16x16x32_bf16 v[32:35], v[168:171], v[184:187], v[32:35]
	v_mfma_f32_16x16x32_bf16 v[24:27], v[160:163], v[192:195], v[24:27]
	v_mfma_f32_16x16x32_bf16 v[16:19], v[168:171], v[192:195], v[16:19]
	v_mfma_f32_16x16x32_bf16 v[8:11], v[160:163], v[200:203], v[8:11]
	v_mfma_f32_16x16x32_bf16 v[0:3], v[168:171], v[200:203], v[0:3]
	v_mfma_f32_16x16x32_bf16 v[56:59], v[164:167], v[180:183], v[56:59]
	v_mfma_f32_16x16x32_bf16 v[48:51], v[172:175], v[180:183], v[48:51]
	v_mfma_f32_16x16x32_bf16 v[40:43], v[164:167], v[188:191], v[40:43]
	v_mfma_f32_16x16x32_bf16 v[32:35], v[172:175], v[188:191], v[32:35]
	v_mfma_f32_16x16x32_bf16 v[24:27], v[164:167], v[196:199], v[24:27]
	v_mfma_f32_16x16x32_bf16 v[16:19], v[172:175], v[196:199], v[16:19]
	v_mfma_f32_16x16x32_bf16 v[8:11], v[164:167], v[204:207], v[8:11]
	v_mfma_f32_16x16x32_bf16 v[0:3], v[172:175], v[204:207], v[0:3]
	s_barrier
	s_add_i32 s8, 0, 0x18000
	s_add_i32 s37, 0, 0x1c000
	v_add_u32_e32 v156, s8, v145
	v_add_u32_e32 v172, s37, v145
	ds_read_b128 v[140:143], v156
	ds_read_b128 v[148:151], v156 offset:1024
	ds_read_b128 v[152:155], v156 offset:2048
	ds_read_b128 v[156:159], v156 offset:3072
	ds_read_b128 v[160:163], v172
	ds_read_b128 v[164:167], v172 offset:1024
	ds_read_b128 v[168:171], v172 offset:2048
	ds_read_b128 v[172:175], v172 offset:3072
	s_add_u32 s64, s64, 0x40000
	s_addc_u32 s65, s65, 0
	s_mov_b32 m0, s20
	v_lshl_add_u64 v[228:229], s[64:65], 0, v[134:135]
	ds_read_b128 v[176:179], v147 offset:32768
	ds_read_b128 v[180:183], v147 offset:33792
	ds_read_b128 v[184:187], v147 offset:34816
	ds_read_b128 v[188:191], v147 offset:35840
	ds_read_b128 v[192:195], v147 offset:36864
	ds_read_b128 v[196:199], v147 offset:37888
	ds_read_b128 v[200:203], v147 offset:38912
	ds_read_b128 v[204:207], v147 offset:39936
	global_load_lds_dwordx4 v[228:229], off
	v_lshl_add_u64 v[228:229], s[64:65], 0, v[132:133]
	s_mov_b32 m0, s21
	s_nop 0
	global_load_lds_dwordx4 v[228:229], off
	s_waitcnt vmcnt(8)
	s_waitcnt lgkmcnt(0)
	s_barrier
	s_waitcnt lgkmcnt(0)
	v_mfma_f32_16x16x32_bf16 v[124:127], v[140:143], v[176:179], v[124:127]
	v_mfma_f32_16x16x32_bf16 v[116:119], v[152:155], v[176:179], v[116:119]
	v_mfma_f32_16x16x32_bf16 v[108:111], v[140:143], v[184:187], v[108:111]
	v_mfma_f32_16x16x32_bf16 v[100:103], v[152:155], v[184:187], v[100:103]
	v_mfma_f32_16x16x32_bf16 v[92:95], v[140:143], v[192:195], v[92:95]
	v_mfma_f32_16x16x32_bf16 v[84:87], v[152:155], v[192:195], v[84:87]
	v_mfma_f32_16x16x32_bf16 v[76:79], v[140:143], v[200:203], v[76:79]
	v_mfma_f32_16x16x32_bf16 v[68:71], v[152:155], v[200:203], v[68:71]
	v_mfma_f32_16x16x32_bf16 v[124:127], v[148:151], v[180:183], v[124:127]
	v_mfma_f32_16x16x32_bf16 v[116:119], v[156:159], v[180:183], v[116:119]
	v_mfma_f32_16x16x32_bf16 v[108:111], v[148:151], v[188:191], v[108:111]
	v_mfma_f32_16x16x32_bf16 v[100:103], v[156:159], v[188:191], v[100:103]
	v_mfma_f32_16x16x32_bf16 v[92:95], v[148:151], v[196:199], v[92:95]
	v_mfma_f32_16x16x32_bf16 v[84:87], v[156:159], v[196:199], v[84:87]
	v_mfma_f32_16x16x32_bf16 v[76:79], v[148:151], v[204:207], v[76:79]
	v_mfma_f32_16x16x32_bf16 v[68:71], v[156:159], v[204:207], v[68:71]
	v_mfma_f32_16x16x32_bf16 v[120:123], v[160:163], v[176:179], v[120:123]
	v_mfma_f32_16x16x32_bf16 v[112:115], v[168:171], v[176:179], v[112:115]
	v_mfma_f32_16x16x32_bf16 v[104:107], v[160:163], v[184:187], v[104:107]
	v_mfma_f32_16x16x32_bf16 v[96:99], v[168:171], v[184:187], v[96:99]
	v_mfma_f32_16x16x32_bf16 v[88:91], v[160:163], v[192:195], v[88:91]
	v_mfma_f32_16x16x32_bf16 v[80:83], v[168:171], v[192:195], v[80:83]
	v_mfma_f32_16x16x32_bf16 v[72:75], v[160:163], v[200:203], v[72:75]
	v_mfma_f32_16x16x32_bf16 v[64:67], v[168:171], v[200:203], v[64:67]
	v_mfma_f32_16x16x32_bf16 v[120:123], v[164:167], v[180:183], v[120:123]
	v_mfma_f32_16x16x32_bf16 v[112:115], v[172:175], v[180:183], v[112:115]
	v_mfma_f32_16x16x32_bf16 v[104:107], v[164:167], v[188:191], v[104:107]
	v_mfma_f32_16x16x32_bf16 v[96:99], v[172:175], v[188:191], v[96:99]
	v_mfma_f32_16x16x32_bf16 v[88:91], v[164:167], v[196:199], v[88:91]
	v_mfma_f32_16x16x32_bf16 v[80:83], v[172:175], v[196:199], v[80:83]
	v_mfma_f32_16x16x32_bf16 v[72:75], v[164:167], v[204:207], v[72:75]
	v_mfma_f32_16x16x32_bf16 v[64:67], v[172:175], v[204:207], v[64:67]
	s_barrier
; #define PG8_STAGE(bufoff, gbase, voff) do { _Pragma("unroll") for (int _i = 0; _i < 2; ++_i) \
;         __builtin_amdgcn_global_load_lds((const unsigned*)((const char*)(gbase) + (voff)[_i]), (PG8_LAS unsigned*)(lds + (bufoff) + ldsw + _i * 8192), 16, 0, 0); } while (0)
; #define PG8_LDA(dst, b, h) do { _Pragma("unroll") for (int m = 0; m < 4; ++m) _Pragma("unroll") for (int k = 0; k < 2; ++k) dst[m][k] = *(const PG8_LAS bf16x8*)(lds + PG8_SA(b, h) + aoff + m * 2048 + k * 1024); } while (0)
; #define PG8_LDB(dst, b, h) do { _Pragma("unroll") for (int n = 0; n < 2; ++n) _Pragma("unroll") for (int k = 0; k < 2; ++k) dst[n][k] = *(const PG8_LAS bf16x8*)(lds + PG8_SB(b, h) + boff + n * 2048 + k * 1024); } while (0)
; #define PG8_MMA(ai, bj, At, Bt) do { __builtin_amdgcn_s_setprio(1); _Pragma("unroll") for (int m = 0; m < 4; ++m) _Pragma("unroll") for (int n = 0; n < 2; ++n) _Pragma("unroll") for (int k = 0; k < 2; ++k) \
;         acc[ai][bj][m][n] = __builtin_amdgcn_mfma_f32_16x16x32_bf16(Bt[n][k], At[m][k], acc[ai][bj][m][n], 0, 0, 0); __builtin_amdgcn_s_setprio(0); } while (0)
; #define PG8_BAR __builtin_amdgcn_s_barrier()
; template <class Epi, class Sched, bool ALIGN_EPI = false, bool SP2 = false>
; __device__ __forceinline__ void gemm_phase(PG8_LAS unsigned char* lds, const Gemm g, const Sched& S, const Epi& E) {
;     ...
;             if constexpr (SP2) {
;             PG8_LDB(B0, 0, 0); PG8_LDB(B1, 0, 1); PG8_SCHED; PG8_LDA(At, 0, 0); PG8_STAGE(PG8_SA(1, 1), a1 + hstep, voffA);
;             PG8_WAIT_V(8); PG8_WAIT_L(0); PG8_BAR; PG8_MMA(0, 0, At, B0); PG8_MMA(0, 1, At, B1); PG8_BAR; PG8_SCHED;
;             PG8_LDA(At, 0, 1); PG8_STAGE(PG8_SB(0, 0), b2, voffB); PG8_STAGE(PG8_SB(0, 1), b2 + hstep, voffB); PG8_STAGE(PG8_SA(0, 0), a2, voffA);
;             PG8_WAIT_V(8); PG8_WAIT_L(0); PG8_BAR; PG8_MMA(1, 0, At, B0); PG8_MMA(1, 1, At, B1); PG8_BAR; PG8_SCHED;
;             PG8_LDB(B0, 1, 0); PG8_LDB(B1, 1, 1); PG8_SCHED; PG8_LDA(At, 1, 0); PG8_STAGE(PG8_SA(0, 1), a2 + hstep, voffA);
;             PG8_WAIT_V(8); PG8_WAIT_L(0); PG8_BAR; PG8_MMA(0, 0, At, B0); PG8_MMA(0, 1, At, B1); PG8_BAR; PG8_SCHED;
;             PG8_LDA(At, 1, 1); PG8_STAGE(PG8_SB(1, 0), b3, voffB); PG8_STAGE(PG8_SB(1, 1), b3 + hstep, voffB); PG8_STAGE(PG8_SA(1, 0), a3, voffA);
;             PG8_WAIT_V(8); PG8_WAIT_L(0); PG8_BAR; PG8_MMA(1, 0, At, B0); PG8_MMA(1, 1, At, B1); PG8_BAR; PG8_SCHED;
	s_add_i32 s8, s8, s17
	v_lshl_add_u64 v[208:209], v[208:209], 0, s[90:91]
	s_mov_b32 m0, s8
	ds_read_b128 v[176:179], v147 offset:49152
	ds_read_b128 v[180:183], v147 offset:50176
	ds_read_b128 v[184:187], v147 offset:51200
	ds_read_b128 v[188:191], v147 offset:52224
	ds_read_b128 v[192:195], v147 offset:53248
	ds_read_b128 v[196:199], v147 offset:54272
	ds_read_b128 v[200:203], v147 offset:55296
	ds_read_b128 v[204:207], v147 offset:56320
	global_load_lds_dwordx4 v[208:209], off
	s_add_i32 m0, s8, 0x2000
	s_add_u32 s58, s58, 0x40080
	v_lshl_add_u64 v[208:209], v[210:211], 0, s[90:91]
	s_addc_u32 s59, s59, 0
	s_add_i32 s8, s37, s17
	global_load_lds_dwordx4 v[208:209], off
	v_lshl_add_u64 v[208:209], s[58:59], 0, v[128:129]
	s_mov_b32 m0, s8
	s_nop 0
	global_load_lds_dwordx4 v[208:209], off
	v_lshl_add_u64 v[208:209], s[58:59], 0, v[130:131]
	s_add_i32 m0, s8, 0x2000
	s_nop 0
	global_load_lds_dwordx4 v[208:209], off
	v_lshl_add_u64 v[208:209], v[214:215], 0, s[90:91]
	s_mov_b32 m0, s22
	s_nop 0
	global_load_lds_dwordx4 v[208:209], off
	v_lshl_add_u64 v[208:209], v[222:223], 0, s[90:91]
	s_mov_b32 m0, s23
	s_nop 0
	global_load_lds_dwordx4 v[208:209], off
	s_waitcnt vmcnt(8)
	s_waitcnt lgkmcnt(0)
	s_barrier
	s_waitcnt lgkmcnt(0)
	v_mfma_f32_16x16x32_bf16 v[60:63], v[140:143], v[176:179], v[60:63]
	v_mfma_f32_16x16x32_bf16 v[52:55], v[152:155], v[176:179], v[52:55]
	v_mfma_f32_16x16x32_bf16 v[44:47], v[140:143], v[184:187], v[44:47]
	v_mfma_f32_16x16x32_bf16 v[36:39], v[152:155], v[184:187], v[36:39]
	v_mfma_f32_16x16x32_bf16 v[28:31], v[140:143], v[192:195], v[28:31]
	v_mfma_f32_16x16x32_bf16 v[20:23], v[152:155], v[192:195], v[20:23]
	v_mfma_f32_16x16x32_bf16 v[12:15], v[140:143], v[200:203], v[12:15]
	v_mfma_f32_16x16x32_bf16 v[4:7], v[152:155], v[200:203], v[4:7]
	v_mfma_f32_16x16x32_bf16 v[60:63], v[148:151], v[180:183], v[60:63]
	v_mfma_f32_16x16x32_bf16 v[52:55], v[156:159], v[180:183], v[52:55]
	v_mfma_f32_16x16x32_bf16 v[44:47], v[148:151], v[188:191], v[44:47]
	v_mfma_f32_16x16x32_bf16 v[36:39], v[156:159], v[188:191], v[36:39]
	v_mfma_f32_16x16x32_bf16 v[28:31], v[148:151], v[196:199], v[28:31]
	v_mfma_f32_16x16x32_bf16 v[20:23], v[156:159], v[196:199], v[20:23]
	v_mfma_f32_16x16x32_bf16 v[12:15], v[148:151], v[204:207], v[12:15]
	v_mfma_f32_16x16x32_bf16 v[4:7], v[156:159], v[204:207], v[4:7]
	v_mfma_f32_16x16x32_bf16 v[56:59], v[160:163], v[176:179], v[56:59]
	v_mfma_f32_16x16x32_bf16 v[48:51], v[168:171], v[176:179], v[48:51]
	v_mfma_f32_16x16x32_bf16 v[40:43], v[160:163], v[184:187], v[40:43]
	v_mfma_f32_16x16x32_bf16 v[32:35], v[168:171], v[184:187], v[32:35]
	v_mfma_f32_16x16x32_bf16 v[24:27], v[160:163], v[192:195], v[24:27]
	v_mfma_f32_16x16x32_bf16 v[16:19], v[168:171], v[192:195], v[16:19]
	v_mfma_f32_16x16x32_bf16 v[8:11], v[160:163], v[200:203], v[8:11]
	v_mfma_f32_16x16x32_bf16 v[0:3], v[168:171], v[200:203], v[0:3]
	v_mfma_f32_16x16x32_bf16 v[56:59], v[164:167], v[180:183], v[56:59]
	v_mfma_f32_16x16x32_bf16 v[48:51], v[172:175], v[180:183], v[48:51]
	v_mfma_f32_16x16x32_bf16 v[40:43], v[164:167], v[188:191], v[40:43]
	v_mfma_f32_16x16x32_bf16 v[32:35], v[172:175], v[188:191], v[32:35]
	v_mfma_f32_16x16x32_bf16 v[24:27], v[164:167], v[196:199], v[24:27]
	v_mfma_f32_16x16x32_bf16 v[16:19], v[172:175], v[196:199], v[16:19]
	v_mfma_f32_16x16x32_bf16 v[8:11], v[164:167], v[204:207], v[8:11]
	v_mfma_f32_16x16x32_bf16 v[0:3], v[172:175], v[204:207], v[0:3]
	s_add_i32 s36, s36, 2
	s_add_u32 s66, s66, 0x100
	s_addc_u32 s67, s67, 0
	s_add_u32 s34, s34, 0x100
	s_addc_u32 s35, s35, 0
